# consolidated: peeled GEMM first iterations + P1 header shift + q/k permlane-swap and sub-LN DPP reductions + direct jumps out of the epilogue variant chain
# speedup vs baseline: 1.0065x; 1.0065x over previous
; __device__ __forceinline__ unsigned long long rt() { return __builtin_amdgcn_s_memrealtime(); }
; __device__ __forceinline__ u32x4 pack8f(const f32x4 a, const f32x4 b) { u32x4 w; w.x = cvt_pk_bf16(a[0], a[1]); w.y = cvt_pk_bf16(a[2], a[3]); w.z = cvt_pk_bf16(b[0], b[1]); w.w = cvt_pk_bf16(b[2], b[3]); return w; }
;     __device__ __forceinline__ void operator()(f32x4 (&acc)[2][2][4][2], const Unit& u, int wr, int wc, int fr, int fq) const {
;         const int b = u.pm >> 4, s0 = (u.pm & 15) * 256, pn = u.pn; int rl0 = wr * 64 + fr; asm volatile("" : "+v"(rl0)); asm volatile("" : "+v"(fq));
;         if (pn < 4) {
;     ...
;             const int j0 = 128 * (pn - 16) + 32 * wc + 8 * fq;
; #pragma unroll
;             for (int ai = 0; ai < 2; ++ai)
; #pragma unroll
;                 for (int m = 0; m < 4; ++m) { const int rl = rl0 + 128 * ai + 16 * m;
;                     f32x4 rt[2], s1[2];
; #pragma unroll
;                     for (int n = 0; n < 2; ++n)
; #pragma unroll
;                         for (int i = 0; i < 4; ++i) {
;                             const float e0 = __builtin_amdgcn_exp2f(fminf(-1.4426950408889634f * acc[ai][0][m][n][i], 60.f)), e1 = __builtin_amdgcn_exp2f(fminf(-1.4426950408889634f * acc[ai][1][m][n][i], 60.f));
;                             rt[n][i] = (1.f + e1) * __builtin_amdgcn_rcpf(1.f + e0); s1[n][i] = __builtin_amdgcn_rcpf(1.f + e1); }
;                     __builtin_nontemporal_store(pack8f(rt[0], rt[1]), (u32x4*)(RT + (size_t)(u.pm * 256 + rl) * DM + j0));
;                     __builtin_nontemporal_store(pack8f(s1[0], s1[1]), (u32x4*)(G1 + (size_t)(u.pm * 256 + rl) * DM + j0));
.LBB0_146:
	s_lshl_b32 s1, s22, 8
	s_ashr_i32 s81, s22, 4
	s_and_b32 s83, s1, 0xf00
	v_mov_b32_e32 v166, v163
	v_mov_b32_e32 v200, v1
	s_cmp_gt_i32 s10, 3
	s_mov_b64 s[88:89], -1
	s_cbranch_scc0 .LBB0_174
	s_cmp_gt_u32 s10, 5
	s_cbranch_scc0 .LBB0_171
	s_cmp_gt_u32 s10, 7
	s_cbranch_scc0 .LBB0_168
	s_cmp_gt_u32 s10, 15
	s_cbranch_scc0 .LBB0_151
	v_mul_f32_e32 v130, 0xbfb8aa3b, v126
	v_min_f32_e32 v130, 0x42700000, v130
	v_exp_f32_e32 v131, v130
	v_mul_f32_e32 v130, 0xbfb8aa3b, v118
	v_min_f32_e32 v130, 0x42700000, v130
	v_exp_f32_e32 v130, v130
	v_add_f32_e32 v131, 1.0, v131
	v_rcp_f32_e32 v132, v131
	v_mul_f32_e32 v131, 0xbfb8aa3b, v127
	v_min_f32_e32 v131, 0x42700000, v131
	v_exp_f32_e32 v133, v131
	v_mul_f32_e32 v131, 0xbfb8aa3b, v119
	v_min_f32_e32 v131, 0x42700000, v131
	v_exp_f32_e32 v131, v131
	v_add_f32_e32 v133, 1.0, v133
	v_rcp_f32_e32 v133, v133
	v_mul_f32_e32 v134, 0xbfb8aa3b, v120
	v_pk_add_f32 v[130:131], v[130:131], 1.0 op_sel_hi:[1,0]
	v_mul_f32_e32 v135, 0xbfb8aa3b, v121
	v_rcp_f32_e32 v154, v130
	v_pk_mul_f32 v[132:133], v[132:133], v[130:131]
	v_mul_f32_e32 v130, 0xbfb8aa3b, v128
	v_min_f32_e32 v130, 0x42700000, v130
	v_exp_f32_e32 v130, v130
	v_min_f32_e32 v134, 0x42700000, v134
	v_min_f32_e32 v135, 0x42700000, v135
	v_exp_f32_e32 v134, v134
	v_add_f32_e32 v130, 1.0, v130
	v_rcp_f32_e32 v136, v130
	v_mul_f32_e32 v130, 0xbfb8aa3b, v129
	v_min_f32_e32 v130, 0x42700000, v130
	v_exp_f32_e32 v130, v130
	v_exp_f32_e32 v135, v135
	v_rcp_f32_e32 v167, v131
	v_mul_f32_e32 v139, 0xbfb8aa3b, v124
	v_add_f32_e32 v130, 1.0, v130
	v_rcp_f32_e32 v137, v130
	v_pk_add_f32 v[130:131], v[134:135], 1.0 op_sel_hi:[1,0]
	v_min_f32_e32 v139, 0x42700000, v139
	v_rcp_f32_e32 v168, v130
	v_pk_mul_f32 v[136:137], v[136:137], v[130:131]
	v_mul_f32_e32 v130, 0xbfb8aa3b, v122
	v_min_f32_e32 v130, 0x42700000, v130
	v_rcp_f32_e32 v169, v131
	v_exp_f32_e32 v131, v130
	v_exp_f32_e32 v139, v139
	v_mul_f32_e32 v130, 0xbfb8aa3b, v114
	v_min_f32_e32 v130, 0x42700000, v130
	v_add_f32_e32 v134, 1.0, v131
	v_mul_f32_e32 v131, 0xbfb8aa3b, v123
	v_add_f32_e32 v139, 1.0, v139
	v_min_f32_e32 v131, 0x42700000, v131
	v_rcp_f32_e32 v142, v139
	v_mul_f32_e32 v139, 0xbfb8aa3b, v125
	v_exp_f32_e32 v135, v131
	v_min_f32_e32 v139, 0x42700000, v139
	v_exp_f32_e32 v139, v139
	v_mul_f32_e32 v131, 0xbfb8aa3b, v115
	v_min_f32_e32 v131, 0x42700000, v131
	v_mul_f32_e32 v140, 0xbfb8aa3b, v116
	v_mul_f32_e32 v141, 0xbfb8aa3b, v117
	v_exp_f32_e32 v130, v130
	v_exp_f32_e32 v131, v131
	v_add_f32_e32 v135, 1.0, v135
	v_min_f32_e32 v140, 0x42700000, v140
	v_min_f32_e32 v141, 0x42700000, v141
	v_rcp_f32_e32 v134, v134
	v_rcp_f32_e32 v135, v135
	v_exp_f32_e32 v140, v140
	v_exp_f32_e32 v141, v141
	v_add_f32_e32 v139, 1.0, v139
	v_rcp_f32_e32 v143, v139
	v_pk_add_f32 v[130:131], v[130:131], 1.0 op_sel_hi:[1,0]
	s_lshl_b32 s11, s10, 7
	v_rcp_f32_e32 v170, v130
	v_pk_mul_f32 v[144:145], v[134:135], v[130:131]
	v_rcp_f32_e32 v171, v131
	v_pk_add_f32 v[130:131], v[140:141], 1.0 op_sel_hi:[1,0]
	v_cvt_pk_bf16_f32 v134, v132, v133
	v_add_u32_e32 v132, s1, v166
	v_pk_mul_f32 v[140:141], v[142:143], v[130:131]
	v_ashrrev_i32_e32 v133, 31, v132
	v_cvt_pk_bf16_f32 v135, v136, v137
	v_cvt_pk_bf16_f32 v137, v140, v141
	v_lshlrev_b64 v[140:141], 11, v[132:133]
	v_mul_f32_e32 v133, 0xbfb8aa3b, v110
	v_min_f32_e32 v133, 0x42700000, v133
	v_exp_f32_e32 v133, v133
	v_lshlrev_b32_e32 v138, 3, v200
	v_readlane_b32 s18, v236, 22
	v_ashrrev_i32_e32 v139, 31, v138
	s_or_b32 s22, s18, s11
	v_rcp_f32_e32 v172, v130
	v_rcp_f32_e32 v173, v131
	v_lshl_add_u64 v[130:131], s[22:23], 0, v[138:139]
	v_lshl_add_u64 v[142:143], s[68:69], 0, v[140:141]
	v_lshlrev_b64 v[130:131], 1, v[130:131]
	v_add_f32_e32 v133, 1.0, v133
	v_lshl_add_u64 v[138:139], v[142:143], 0, v[130:131]
	v_rcp_f32_e32 v142, v133
	v_mul_f32_e32 v133, 0xbfb8aa3b, v111
	v_min_f32_e32 v133, 0x42700000, v133
	v_exp_f32_e32 v133, v133
	v_cvt_pk_bf16_f32 v136, v144, v145
	global_store_dwordx4 v[138:139], v[134:137], off offset:-4096 nt
	v_lshl_add_u64 v[138:139], s[70:71], 0, v[140:141]
	v_add_f32_e32 v133, 1.0, v133
	v_rcp_f32_e32 v143, v133
	v_mul_f32_e32 v133, 0xbfb8aa3b, v112
	v_mul_f32_e32 v140, 0xbfb8aa3b, v102
	v_mul_f32_e32 v141, 0xbfb8aa3b, v103
	v_min_f32_e32 v133, 0x42700000, v133
	v_min_f32_e32 v140, 0x42700000, v140
	v_min_f32_e32 v141, 0x42700000, v141
	v_exp_f32_e32 v133, v133
	v_exp_f32_e32 v140, v140
	v_exp_f32_e32 v141, v141
	v_cvt_pk_bf16_f32 v134, v154, v167
	v_cvt_pk_bf16_f32 v135, v168, v169
	v_cvt_pk_bf16_f32 v136, v170, v171
	v_cvt_pk_bf16_f32 v137, v172, v173
	v_lshl_add_u64 v[138:139], v[138:139], 0, v[130:131]
	v_add_f32_e32 v133, 1.0, v133
	global_store_dwordx4 v[138:139], v[134:137], off offset:-4096 nt
	v_mul_f32_e32 v138, 0xbfb8aa3b, v104
	v_mul_f32_e32 v139, 0xbfb8aa3b, v105
	v_pk_add_f32 v[134:135], v[140:141], 1.0 op_sel_hi:[1,0]
	v_rcp_f32_e32 v140, v133
	v_mul_f32_e32 v133, 0xbfb8aa3b, v113
	v_min_f32_e32 v133, 0x42700000, v133
	v_exp_f32_e32 v133, v133
	v_min_f32_e32 v138, 0x42700000, v138
	v_min_f32_e32 v139, 0x42700000, v139
	v_exp_f32_e32 v138, v138
	v_exp_f32_e32 v139, v139
	v_add_f32_e32 v133, 1.0, v133
	v_rcp_f32_e32 v141, v133
	v_pk_mul_f32 v[136:137], v[142:143], v[134:135]
	v_rcp_f32_e32 v133, v134
	v_rcp_f32_e32 v154, v135
	v_pk_add_f32 v[134:135], v[138:139], 1.0 op_sel_hi:[1,0]
	s_mov_b64 s[88:89], 0
	v_pk_mul_f32 v[138:139], v[140:141], v[134:135]
	v_mul_f32_e32 v140, 0xbfb8aa3b, v106
	v_min_f32_e32 v140, 0x42700000, v140
	v_exp_f32_e32 v141, v140
	v_mul_f32_e32 v140, 0xbfb8aa3b, v98
	v_min_f32_e32 v140, 0x42700000, v140
	v_exp_f32_e32 v140, v140
	v_add_f32_e32 v141, 1.0, v141
	v_rcp_f32_e32 v142, v141
; __device__ __forceinline__ unsigned long long rt() { return __builtin_amdgcn_s_memrealtime(); }
; __device__ __forceinline__ u32x4 pack8f(const f32x4 a, const f32x4 b) { u32x4 w; w.x = cvt_pk_bf16(a[0], a[1]); w.y = cvt_pk_bf16(a[2], a[3]); w.z = cvt_pk_bf16(b[0], b[1]); w.w = cvt_pk_bf16(b[2], b[3]); return w; }
;     __device__ __forceinline__ void operator()(f32x4 (&acc)[2][2][4][2], const Unit& u, int wr, int wc, int fr, int fq) const {
;     ...
;                     f32x4 rt[2], s1[2];
; #pragma unroll
;                     for (int n = 0; n < 2; ++n)
; #pragma unroll
;                         for (int i = 0; i < 4; ++i) {
;                             const float e0 = __builtin_amdgcn_exp2f(fminf(-1.4426950408889634f * acc[ai][0][m][n][i], 60.f)), e1 = __builtin_amdgcn_exp2f(fminf(-1.4426950408889634f * acc[ai][1][m][n][i], 60.f));
;                             rt[n][i] = (1.f + e1) * __builtin_amdgcn_rcpf(1.f + e0); s1[n][i] = __builtin_amdgcn_rcpf(1.f + e1); }
;                     __builtin_nontemporal_store(pack8f(rt[0], rt[1]), (u32x4*)(RT + (size_t)(u.pm * 256 + rl) * DM + j0));
;                     __builtin_nontemporal_store(pack8f(s1[0], s1[1]), (u32x4*)(G1 + (size_t)(u.pm * 256 + rl) * DM + j0));
	v_mul_f32_e32 v141, 0xbfb8aa3b, v107
	v_min_f32_e32 v141, 0x42700000, v141
	v_exp_f32_e32 v143, v141
	v_mul_f32_e32 v141, 0xbfb8aa3b, v99
	v_min_f32_e32 v141, 0x42700000, v141
	v_exp_f32_e32 v141, v141
	v_add_f32_e32 v143, 1.0, v143
	v_rcp_f32_e32 v143, v143
	v_rcp_f32_e32 v167, v134
	v_rcp_f32_e32 v168, v135
	v_pk_add_f32 v[134:135], v[140:141], 1.0 op_sel_hi:[1,0]
	s_nop 0
	v_pk_mul_f32 v[140:141], v[142:143], v[134:135]
	v_mul_f32_e32 v142, 0xbfb8aa3b, v108
	v_min_f32_e32 v142, 0x42700000, v142
	v_exp_f32_e32 v143, v142
	v_mul_f32_e32 v142, 0xbfb8aa3b, v100
	v_min_f32_e32 v142, 0x42700000, v142
	v_exp_f32_e32 v142, v142
	v_add_f32_e32 v143, 1.0, v143
	v_rcp_f32_e32 v144, v143
	v_mul_f32_e32 v143, 0xbfb8aa3b, v109
	v_min_f32_e32 v143, 0x42700000, v143
	v_exp_f32_e32 v145, v143
	v_mul_f32_e32 v143, 0xbfb8aa3b, v101
	v_min_f32_e32 v143, 0x42700000, v143
	v_exp_f32_e32 v143, v143
	v_add_f32_e32 v145, 1.0, v145
	v_rcp_f32_e32 v145, v145
	v_rcp_f32_e32 v169, v134
	v_rcp_f32_e32 v170, v135
	v_pk_add_f32 v[134:135], v[142:143], 1.0 op_sel_hi:[1,0]
	s_nop 0
	v_pk_mul_f32 v[142:143], v[144:145], v[134:135]
	v_rcp_f32_e32 v145, v135
	v_cvt_pk_bf16_f32 v135, v138, v139
	v_add_u32_e32 v138, 16, v132
	v_ashrrev_i32_e32 v139, 31, v138
	v_lshlrev_b64 v[138:139], 11, v[138:139]
	v_rcp_f32_e32 v144, v134
	v_cvt_pk_bf16_f32 v134, v136, v137
	v_cvt_pk_bf16_f32 v136, v140, v141
	v_lshl_add_u64 v[140:141], s[68:69], 0, v[138:139]
	v_cvt_pk_bf16_f32 v137, v142, v143
	v_lshl_add_u64 v[140:141], v[140:141], 0, v[130:131]
	global_store_dwordx4 v[140:141], v[134:137], off offset:-4096 nt
	v_mul_f32_e32 v140, 0xbfb8aa3b, v86
	v_mul_f32_e32 v141, 0xbfb8aa3b, v87
	v_cvt_pk_bf16_f32 v134, v133, v154
	v_mul_f32_e32 v133, 0xbfb8aa3b, v94
	v_min_f32_e32 v133, 0x42700000, v133
	v_exp_f32_e32 v133, v133
	v_min_f32_e32 v140, 0x42700000, v140
	v_min_f32_e32 v141, 0x42700000, v141
	v_exp_f32_e32 v140, v140
	v_add_f32_e32 v133, 1.0, v133
	v_rcp_f32_e32 v142, v133
	v_mul_f32_e32 v133, 0xbfb8aa3b, v95
	v_min_f32_e32 v133, 0x42700000, v133
	v_exp_f32_e32 v133, v133
	v_exp_f32_e32 v141, v141
	v_lshl_add_u64 v[138:139], s[70:71], 0, v[138:139]
	v_cvt_pk_bf16_f32 v135, v167, v168
	v_add_f32_e32 v133, 1.0, v133
	v_rcp_f32_e32 v143, v133
	v_mul_f32_e32 v133, 0xbfb8aa3b, v96
	v_min_f32_e32 v133, 0x42700000, v133
	v_exp_f32_e32 v133, v133
	v_cvt_pk_bf16_f32 v136, v169, v170
	v_cvt_pk_bf16_f32 v137, v144, v145
	v_lshl_add_u64 v[138:139], v[138:139], 0, v[130:131]
	v_add_f32_e32 v133, 1.0, v133
	global_store_dwordx4 v[138:139], v[134:137], off offset:-4096 nt
	v_mul_f32_e32 v138, 0xbfb8aa3b, v88
	v_mul_f32_e32 v139, 0xbfb8aa3b, v89
	v_pk_add_f32 v[134:135], v[140:141], 1.0 op_sel_hi:[1,0]
	v_rcp_f32_e32 v140, v133
	v_mul_f32_e32 v133, 0xbfb8aa3b, v97
	v_min_f32_e32 v133, 0x42700000, v133
	v_exp_f32_e32 v133, v133
	v_min_f32_e32 v138, 0x42700000, v138
	v_min_f32_e32 v139, 0x42700000, v139
	v_exp_f32_e32 v138, v138
	v_exp_f32_e32 v139, v139
	v_add_f32_e32 v133, 1.0, v133
	v_rcp_f32_e32 v141, v133
	v_pk_mul_f32 v[136:137], v[142:143], v[134:135]
	v_rcp_f32_e32 v133, v134
	v_rcp_f32_e32 v154, v135
	v_pk_add_f32 v[134:135], v[138:139], 1.0 op_sel_hi:[1,0]
	s_nop 0
	v_pk_mul_f32 v[138:139], v[140:141], v[134:135]
	v_mul_f32_e32 v140, 0xbfb8aa3b, v90
	v_min_f32_e32 v140, 0x42700000, v140
	v_exp_f32_e32 v141, v140
	v_mul_f32_e32 v140, 0xbfb8aa3b, v82
	v_min_f32_e32 v140, 0x42700000, v140
	v_exp_f32_e32 v140, v140
	v_add_f32_e32 v141, 1.0, v141
	v_rcp_f32_e32 v142, v141
	v_mul_f32_e32 v141, 0xbfb8aa3b, v91
	v_min_f32_e32 v141, 0x42700000, v141
	v_exp_f32_e32 v143, v141
	v_mul_f32_e32 v141, 0xbfb8aa3b, v83
	v_min_f32_e32 v141, 0x42700000, v141
	v_exp_f32_e32 v141, v141
	v_add_f32_e32 v143, 1.0, v143
	v_rcp_f32_e32 v143, v143
	v_rcp_f32_e32 v167, v134
	v_rcp_f32_e32 v168, v135
	v_pk_add_f32 v[134:135], v[140:141], 1.0 op_sel_hi:[1,0]
	s_nop 0
	v_pk_mul_f32 v[140:141], v[142:143], v[134:135]
	v_mul_f32_e32 v142, 0xbfb8aa3b, v92
	v_min_f32_e32 v142, 0x42700000, v142
	v_exp_f32_e32 v143, v142
	v_mul_f32_e32 v142, 0xbfb8aa3b, v84
	v_min_f32_e32 v142, 0x42700000, v142
	v_exp_f32_e32 v142, v142
	v_add_f32_e32 v143, 1.0, v143
	v_rcp_f32_e32 v144, v143
	v_mul_f32_e32 v143, 0xbfb8aa3b, v93
	v_min_f32_e32 v143, 0x42700000, v143
	v_exp_f32_e32 v145, v143
	v_mul_f32_e32 v143, 0xbfb8aa3b, v85
	v_min_f32_e32 v143, 0x42700000, v143
	v_exp_f32_e32 v143, v143
	v_add_f32_e32 v145, 1.0, v145
	v_rcp_f32_e32 v145, v145
	v_rcp_f32_e32 v169, v134
	v_rcp_f32_e32 v170, v135
	v_pk_add_f32 v[134:135], v[142:143], 1.0 op_sel_hi:[1,0]
	s_nop 0
	v_pk_mul_f32 v[142:143], v[144:145], v[134:135]
	v_rcp_f32_e32 v145, v135
	v_cvt_pk_bf16_f32 v135, v138, v139
	v_add_u32_e32 v138, 32, v132
	v_ashrrev_i32_e32 v139, 31, v138
	v_lshlrev_b64 v[138:139], 11, v[138:139]
	v_rcp_f32_e32 v144, v134
	v_cvt_pk_bf16_f32 v134, v136, v137
	v_cvt_pk_bf16_f32 v136, v140, v141
	v_lshl_add_u64 v[140:141], s[68:69], 0, v[138:139]
	v_cvt_pk_bf16_f32 v137, v142, v143
	v_lshl_add_u64 v[140:141], v[140:141], 0, v[130:131]
	global_store_dwordx4 v[140:141], v[134:137], off offset:-4096 nt
	v_mul_f32_e32 v140, 0xbfb8aa3b, v70
	v_mul_f32_e32 v141, 0xbfb8aa3b, v71
	v_cvt_pk_bf16_f32 v134, v133, v154
	v_mul_f32_e32 v133, 0xbfb8aa3b, v78
	v_min_f32_e32 v133, 0x42700000, v133
	v_exp_f32_e32 v133, v133
	v_min_f32_e32 v140, 0x42700000, v140
	v_min_f32_e32 v141, 0x42700000, v141
	v_exp_f32_e32 v140, v140
	v_add_f32_e32 v133, 1.0, v133
	v_rcp_f32_e32 v142, v133
	v_mul_f32_e32 v133, 0xbfb8aa3b, v79
	v_min_f32_e32 v133, 0x42700000, v133
	v_exp_f32_e32 v133, v133
	v_exp_f32_e32 v141, v141
	v_lshl_add_u64 v[138:139], s[70:71], 0, v[138:139]
	v_cvt_pk_bf16_f32 v135, v167, v168
; __device__ __forceinline__ unsigned long long rt() { return __builtin_amdgcn_s_memrealtime(); }
; __device__ __forceinline__ u32x4 pack8f(const f32x4 a, const f32x4 b) { u32x4 w; w.x = cvt_pk_bf16(a[0], a[1]); w.y = cvt_pk_bf16(a[2], a[3]); w.z = cvt_pk_bf16(b[0], b[1]); w.w = cvt_pk_bf16(b[2], b[3]); return w; }
;     __device__ __forceinline__ void operator()(f32x4 (&acc)[2][2][4][2], const Unit& u, int wr, int wc, int fr, int fq) const {
;     ...
;                     f32x4 rt[2], s1[2];
; #pragma unroll
;                     for (int n = 0; n < 2; ++n)
; #pragma unroll
;                         for (int i = 0; i < 4; ++i) {
;                             const float e0 = __builtin_amdgcn_exp2f(fminf(-1.4426950408889634f * acc[ai][0][m][n][i], 60.f)), e1 = __builtin_amdgcn_exp2f(fminf(-1.4426950408889634f * acc[ai][1][m][n][i], 60.f));
;                             rt[n][i] = (1.f + e1) * __builtin_amdgcn_rcpf(1.f + e0); s1[n][i] = __builtin_amdgcn_rcpf(1.f + e1); }
;                     __builtin_nontemporal_store(pack8f(rt[0], rt[1]), (u32x4*)(RT + (size_t)(u.pm * 256 + rl) * DM + j0));
;                     __builtin_nontemporal_store(pack8f(s1[0], s1[1]), (u32x4*)(G1 + (size_t)(u.pm * 256 + rl) * DM + j0));
	v_add_f32_e32 v133, 1.0, v133
	v_rcp_f32_e32 v143, v133
	v_mul_f32_e32 v133, 0xbfb8aa3b, v80
	v_min_f32_e32 v133, 0x42700000, v133
	v_exp_f32_e32 v133, v133
	v_cvt_pk_bf16_f32 v136, v169, v170
	v_cvt_pk_bf16_f32 v137, v144, v145
	v_lshl_add_u64 v[138:139], v[138:139], 0, v[130:131]
	v_add_f32_e32 v133, 1.0, v133
	global_store_dwordx4 v[138:139], v[134:137], off offset:-4096 nt
	v_mul_f32_e32 v138, 0xbfb8aa3b, v72
	v_mul_f32_e32 v139, 0xbfb8aa3b, v73
	v_pk_add_f32 v[134:135], v[140:141], 1.0 op_sel_hi:[1,0]
	v_rcp_f32_e32 v140, v133
	v_mul_f32_e32 v133, 0xbfb8aa3b, v81
	v_min_f32_e32 v133, 0x42700000, v133
	v_exp_f32_e32 v133, v133
	v_min_f32_e32 v138, 0x42700000, v138
	v_min_f32_e32 v139, 0x42700000, v139
	v_exp_f32_e32 v138, v138
	v_exp_f32_e32 v139, v139
	v_add_f32_e32 v133, 1.0, v133
	v_rcp_f32_e32 v141, v133
	v_pk_mul_f32 v[136:137], v[142:143], v[134:135]
	v_rcp_f32_e32 v133, v134
	v_rcp_f32_e32 v154, v135
	v_pk_add_f32 v[134:135], v[138:139], 1.0 op_sel_hi:[1,0]
	s_nop 0
	v_pk_mul_f32 v[138:139], v[140:141], v[134:135]
	v_mul_f32_e32 v140, 0xbfb8aa3b, v74
	v_min_f32_e32 v140, 0x42700000, v140
	v_exp_f32_e32 v141, v140
	v_mul_f32_e32 v140, 0xbfb8aa3b, v66
	v_min_f32_e32 v140, 0x42700000, v140
	v_exp_f32_e32 v140, v140
	v_add_f32_e32 v141, 1.0, v141
	v_rcp_f32_e32 v142, v141
	v_mul_f32_e32 v141, 0xbfb8aa3b, v75
	v_min_f32_e32 v141, 0x42700000, v141
	v_exp_f32_e32 v143, v141
	v_mul_f32_e32 v141, 0xbfb8aa3b, v67
	v_min_f32_e32 v141, 0x42700000, v141
	v_exp_f32_e32 v141, v141
	v_add_f32_e32 v143, 1.0, v143
	v_rcp_f32_e32 v143, v143
	v_rcp_f32_e32 v167, v134
	v_rcp_f32_e32 v168, v135
	v_pk_add_f32 v[134:135], v[140:141], 1.0 op_sel_hi:[1,0]
	s_nop 0
	v_pk_mul_f32 v[140:141], v[142:143], v[134:135]
	v_mul_f32_e32 v142, 0xbfb8aa3b, v76
	v_min_f32_e32 v142, 0x42700000, v142
	v_exp_f32_e32 v143, v142
	v_mul_f32_e32 v142, 0xbfb8aa3b, v68
	v_min_f32_e32 v142, 0x42700000, v142
	v_exp_f32_e32 v142, v142
	v_add_f32_e32 v143, 1.0, v143
	v_rcp_f32_e32 v144, v143
	v_mul_f32_e32 v143, 0xbfb8aa3b, v77
	v_min_f32_e32 v143, 0x42700000, v143
	v_exp_f32_e32 v145, v143
	v_mul_f32_e32 v143, 0xbfb8aa3b, v69
	v_min_f32_e32 v143, 0x42700000, v143
	v_exp_f32_e32 v143, v143
	v_add_f32_e32 v145, 1.0, v145
	v_rcp_f32_e32 v145, v145
	v_rcp_f32_e32 v169, v134
	v_rcp_f32_e32 v170, v135
	v_pk_add_f32 v[134:135], v[142:143], 1.0 op_sel_hi:[1,0]
	s_nop 0
	v_pk_mul_f32 v[142:143], v[144:145], v[134:135]
	v_rcp_f32_e32 v145, v135
	v_cvt_pk_bf16_f32 v135, v138, v139
	v_add_u32_e32 v138, 48, v132
	v_ashrrev_i32_e32 v139, 31, v138
	v_lshlrev_b64 v[138:139], 11, v[138:139]
	v_rcp_f32_e32 v144, v134
	v_cvt_pk_bf16_f32 v134, v136, v137
	v_cvt_pk_bf16_f32 v136, v140, v141
	v_lshl_add_u64 v[140:141], s[68:69], 0, v[138:139]
	v_cvt_pk_bf16_f32 v137, v142, v143
	v_lshl_add_u64 v[140:141], v[140:141], 0, v[130:131]
	global_store_dwordx4 v[140:141], v[134:137], off offset:-4096 nt
	v_mul_f32_e32 v140, 0xbfb8aa3b, v54
	v_mul_f32_e32 v141, 0xbfb8aa3b, v55
	v_cvt_pk_bf16_f32 v134, v133, v154
	v_mul_f32_e32 v133, 0xbfb8aa3b, v62
	v_min_f32_e32 v133, 0x42700000, v133
	v_exp_f32_e32 v133, v133
	v_min_f32_e32 v140, 0x42700000, v140
	v_min_f32_e32 v141, 0x42700000, v141
	v_exp_f32_e32 v140, v140
	v_add_f32_e32 v133, 1.0, v133
	v_rcp_f32_e32 v142, v133
	v_mul_f32_e32 v133, 0xbfb8aa3b, v63
	v_min_f32_e32 v133, 0x42700000, v133
	v_exp_f32_e32 v133, v133
	v_exp_f32_e32 v141, v141
	v_lshl_add_u64 v[138:139], s[70:71], 0, v[138:139]
	v_cvt_pk_bf16_f32 v135, v167, v168
	v_add_f32_e32 v133, 1.0, v133
	v_rcp_f32_e32 v143, v133
	v_mul_f32_e32 v133, 0xbfb8aa3b, v64
	v_min_f32_e32 v133, 0x42700000, v133
	v_exp_f32_e32 v133, v133
	v_cvt_pk_bf16_f32 v136, v169, v170
	v_cvt_pk_bf16_f32 v137, v144, v145
	v_lshl_add_u64 v[138:139], v[138:139], 0, v[130:131]
	v_add_f32_e32 v133, 1.0, v133
	global_store_dwordx4 v[138:139], v[134:137], off offset:-4096 nt
	v_mul_f32_e32 v138, 0xbfb8aa3b, v56
	v_mul_f32_e32 v139, 0xbfb8aa3b, v57
	v_pk_add_f32 v[134:135], v[140:141], 1.0 op_sel_hi:[1,0]
	v_rcp_f32_e32 v140, v133
	v_mul_f32_e32 v133, 0xbfb8aa3b, v65
	v_min_f32_e32 v133, 0x42700000, v133
	v_exp_f32_e32 v133, v133
	v_min_f32_e32 v138, 0x42700000, v138
	v_min_f32_e32 v139, 0x42700000, v139
	v_exp_f32_e32 v138, v138
	v_exp_f32_e32 v139, v139
	v_add_f32_e32 v133, 1.0, v133
	v_rcp_f32_e32 v141, v133
	v_pk_mul_f32 v[136:137], v[142:143], v[134:135]
	v_rcp_f32_e32 v133, v134
	v_rcp_f32_e32 v154, v135
	v_pk_add_f32 v[134:135], v[138:139], 1.0 op_sel_hi:[1,0]
	s_nop 0
	v_pk_mul_f32 v[138:139], v[140:141], v[134:135]
	v_mul_f32_e32 v140, 0xbfb8aa3b, v58
	v_min_f32_e32 v140, 0x42700000, v140
	v_exp_f32_e32 v141, v140
	v_mul_f32_e32 v140, 0xbfb8aa3b, v50
	v_min_f32_e32 v140, 0x42700000, v140
	v_exp_f32_e32 v140, v140
	v_add_f32_e32 v141, 1.0, v141
	v_rcp_f32_e32 v142, v141
	v_mul_f32_e32 v141, 0xbfb8aa3b, v59
	v_min_f32_e32 v141, 0x42700000, v141
	v_exp_f32_e32 v143, v141
	v_mul_f32_e32 v141, 0xbfb8aa3b, v51
	v_min_f32_e32 v141, 0x42700000, v141
	v_exp_f32_e32 v141, v141
	v_add_f32_e32 v143, 1.0, v143
	v_rcp_f32_e32 v143, v143
	v_rcp_f32_e32 v167, v134
	v_rcp_f32_e32 v168, v135
	v_pk_add_f32 v[134:135], v[140:141], 1.0 op_sel_hi:[1,0]
	s_nop 0
	v_pk_mul_f32 v[140:141], v[142:143], v[134:135]
	v_mul_f32_e32 v142, 0xbfb8aa3b, v60
	v_min_f32_e32 v142, 0x42700000, v142
	v_exp_f32_e32 v143, v142
	v_mul_f32_e32 v142, 0xbfb8aa3b, v52
	v_min_f32_e32 v142, 0x42700000, v142
	v_exp_f32_e32 v142, v142
	v_add_f32_e32 v143, 1.0, v143
	v_rcp_f32_e32 v144, v143
	v_mul_f32_e32 v143, 0xbfb8aa3b, v61
	v_min_f32_e32 v143, 0x42700000, v143
	v_exp_f32_e32 v145, v143
	v_mul_f32_e32 v143, 0xbfb8aa3b, v53
	v_min_f32_e32 v143, 0x42700000, v143
; __device__ __forceinline__ unsigned long long rt() { return __builtin_amdgcn_s_memrealtime(); }
; __device__ __forceinline__ u32x4 pack8f(const f32x4 a, const f32x4 b) { u32x4 w; w.x = cvt_pk_bf16(a[0], a[1]); w.y = cvt_pk_bf16(a[2], a[3]); w.z = cvt_pk_bf16(b[0], b[1]); w.w = cvt_pk_bf16(b[2], b[3]); return w; }
;     __device__ __forceinline__ void operator()(f32x4 (&acc)[2][2][4][2], const Unit& u, int wr, int wc, int fr, int fq) const {
;     ...
;                     f32x4 rt[2], s1[2];
; #pragma unroll
;                     for (int n = 0; n < 2; ++n)
; #pragma unroll
;                         for (int i = 0; i < 4; ++i) {
;                             const float e0 = __builtin_amdgcn_exp2f(fminf(-1.4426950408889634f * acc[ai][0][m][n][i], 60.f)), e1 = __builtin_amdgcn_exp2f(fminf(-1.4426950408889634f * acc[ai][1][m][n][i], 60.f));
;                             rt[n][i] = (1.f + e1) * __builtin_amdgcn_rcpf(1.f + e0); s1[n][i] = __builtin_amdgcn_rcpf(1.f + e1); }
;                     __builtin_nontemporal_store(pack8f(rt[0], rt[1]), (u32x4*)(RT + (size_t)(u.pm * 256 + rl) * DM + j0));
;                     __builtin_nontemporal_store(pack8f(s1[0], s1[1]), (u32x4*)(G1 + (size_t)(u.pm * 256 + rl) * DM + j0));
	v_exp_f32_e32 v143, v143
	v_add_f32_e32 v145, 1.0, v145
	v_rcp_f32_e32 v145, v145
	v_rcp_f32_e32 v169, v134
	v_rcp_f32_e32 v170, v135
	v_pk_add_f32 v[134:135], v[142:143], 1.0 op_sel_hi:[1,0]
	s_nop 0
	v_pk_mul_f32 v[142:143], v[144:145], v[134:135]
	v_rcp_f32_e32 v145, v135
	v_cvt_pk_bf16_f32 v135, v138, v139
	v_add_u32_e32 v138, 0x80, v132
	v_ashrrev_i32_e32 v139, 31, v138
	v_lshlrev_b64 v[138:139], 11, v[138:139]
	v_rcp_f32_e32 v144, v134
	v_cvt_pk_bf16_f32 v134, v136, v137
	v_cvt_pk_bf16_f32 v136, v140, v141
	v_lshl_add_u64 v[140:141], s[68:69], 0, v[138:139]
	v_cvt_pk_bf16_f32 v137, v142, v143
	v_lshl_add_u64 v[140:141], v[140:141], 0, v[130:131]
	global_store_dwordx4 v[140:141], v[134:137], off offset:-4096 nt
	v_mul_f32_e32 v140, 0xbfb8aa3b, v38
	v_mul_f32_e32 v141, 0xbfb8aa3b, v39
	v_cvt_pk_bf16_f32 v134, v133, v154
	v_mul_f32_e32 v133, 0xbfb8aa3b, v46
	v_min_f32_e32 v133, 0x42700000, v133
	v_exp_f32_e32 v133, v133
	v_min_f32_e32 v140, 0x42700000, v140
	v_min_f32_e32 v141, 0x42700000, v141
	v_exp_f32_e32 v140, v140
	v_add_f32_e32 v133, 1.0, v133
	v_rcp_f32_e32 v142, v133
	v_mul_f32_e32 v133, 0xbfb8aa3b, v47
	v_min_f32_e32 v133, 0x42700000, v133
	v_exp_f32_e32 v133, v133
	v_exp_f32_e32 v141, v141
	v_lshl_add_u64 v[138:139], s[70:71], 0, v[138:139]
	v_cvt_pk_bf16_f32 v135, v167, v168
	v_add_f32_e32 v133, 1.0, v133
	v_rcp_f32_e32 v143, v133
	v_mul_f32_e32 v133, 0xbfb8aa3b, v48
	v_min_f32_e32 v133, 0x42700000, v133
	v_exp_f32_e32 v133, v133
	v_cvt_pk_bf16_f32 v136, v169, v170
	v_cvt_pk_bf16_f32 v137, v144, v145
	v_lshl_add_u64 v[138:139], v[138:139], 0, v[130:131]
	v_add_f32_e32 v133, 1.0, v133
	global_store_dwordx4 v[138:139], v[134:137], off offset:-4096 nt
	v_mul_f32_e32 v138, 0xbfb8aa3b, v40
	v_mul_f32_e32 v139, 0xbfb8aa3b, v41
	v_pk_add_f32 v[134:135], v[140:141], 1.0 op_sel_hi:[1,0]
	v_rcp_f32_e32 v140, v133
	v_mul_f32_e32 v133, 0xbfb8aa3b, v49
	v_min_f32_e32 v133, 0x42700000, v133
	v_exp_f32_e32 v133, v133
	v_min_f32_e32 v138, 0x42700000, v138
	v_min_f32_e32 v139, 0x42700000, v139
	v_exp_f32_e32 v138, v138
	v_exp_f32_e32 v139, v139
	v_add_f32_e32 v133, 1.0, v133
	v_rcp_f32_e32 v141, v133
	v_pk_mul_f32 v[136:137], v[142:143], v[134:135]
	v_rcp_f32_e32 v133, v134
	v_rcp_f32_e32 v154, v135
	v_pk_add_f32 v[134:135], v[138:139], 1.0 op_sel_hi:[1,0]
	s_nop 0
	v_pk_mul_f32 v[138:139], v[140:141], v[134:135]
	v_mul_f32_e32 v140, 0xbfb8aa3b, v42
	v_min_f32_e32 v140, 0x42700000, v140
	v_exp_f32_e32 v141, v140
	v_mul_f32_e32 v140, 0xbfb8aa3b, v34
	v_min_f32_e32 v140, 0x42700000, v140
	v_exp_f32_e32 v140, v140
	v_add_f32_e32 v141, 1.0, v141
	v_rcp_f32_e32 v142, v141
	v_mul_f32_e32 v141, 0xbfb8aa3b, v43
	v_min_f32_e32 v141, 0x42700000, v141
	v_exp_f32_e32 v143, v141
	v_mul_f32_e32 v141, 0xbfb8aa3b, v35
	v_min_f32_e32 v141, 0x42700000, v141
	v_exp_f32_e32 v141, v141
	v_add_f32_e32 v143, 1.0, v143
	v_rcp_f32_e32 v143, v143
	v_rcp_f32_e32 v167, v134
	v_rcp_f32_e32 v168, v135
	v_pk_add_f32 v[134:135], v[140:141], 1.0 op_sel_hi:[1,0]
	s_nop 0
	v_pk_mul_f32 v[140:141], v[142:143], v[134:135]
	v_mul_f32_e32 v142, 0xbfb8aa3b, v44
	v_min_f32_e32 v142, 0x42700000, v142
	v_exp_f32_e32 v143, v142
	v_mul_f32_e32 v142, 0xbfb8aa3b, v36
	v_min_f32_e32 v142, 0x42700000, v142
	v_exp_f32_e32 v142, v142
	v_add_f32_e32 v143, 1.0, v143
	v_rcp_f32_e32 v144, v143
	v_mul_f32_e32 v143, 0xbfb8aa3b, v45
	v_min_f32_e32 v143, 0x42700000, v143
	v_exp_f32_e32 v145, v143
	v_mul_f32_e32 v143, 0xbfb8aa3b, v37
	v_min_f32_e32 v143, 0x42700000, v143
	v_exp_f32_e32 v143, v143
	v_add_f32_e32 v145, 1.0, v145
	v_rcp_f32_e32 v145, v145
	v_rcp_f32_e32 v169, v134
	v_rcp_f32_e32 v170, v135
	v_pk_add_f32 v[134:135], v[142:143], 1.0 op_sel_hi:[1,0]
	s_nop 0
	v_pk_mul_f32 v[142:143], v[144:145], v[134:135]
	v_rcp_f32_e32 v145, v135
	v_cvt_pk_bf16_f32 v135, v138, v139
	v_add_u32_e32 v138, 0x90, v132
	v_ashrrev_i32_e32 v139, 31, v138
	v_lshlrev_b64 v[138:139], 11, v[138:139]
	v_rcp_f32_e32 v144, v134
	v_cvt_pk_bf16_f32 v134, v136, v137
	v_cvt_pk_bf16_f32 v136, v140, v141
	v_lshl_add_u64 v[140:141], s[68:69], 0, v[138:139]
	v_cvt_pk_bf16_f32 v137, v142, v143
	v_lshl_add_u64 v[140:141], v[140:141], 0, v[130:131]
	global_store_dwordx4 v[140:141], v[134:137], off offset:-4096 nt
	v_mul_f32_e32 v140, 0xbfb8aa3b, v22
	v_mul_f32_e32 v141, 0xbfb8aa3b, v23
	v_cvt_pk_bf16_f32 v134, v133, v154
	v_mul_f32_e32 v133, 0xbfb8aa3b, v30
	v_min_f32_e32 v133, 0x42700000, v133
	v_exp_f32_e32 v133, v133
	v_min_f32_e32 v140, 0x42700000, v140
	v_min_f32_e32 v141, 0x42700000, v141
	v_exp_f32_e32 v140, v140
	v_add_f32_e32 v133, 1.0, v133
	v_rcp_f32_e32 v142, v133
	v_mul_f32_e32 v133, 0xbfb8aa3b, v31
	v_min_f32_e32 v133, 0x42700000, v133
	v_exp_f32_e32 v133, v133
	v_exp_f32_e32 v141, v141
	v_lshl_add_u64 v[138:139], s[70:71], 0, v[138:139]
	v_cvt_pk_bf16_f32 v135, v167, v168
	v_add_f32_e32 v133, 1.0, v133
	v_rcp_f32_e32 v143, v133
	v_mul_f32_e32 v133, 0xbfb8aa3b, v32
	v_min_f32_e32 v133, 0x42700000, v133
	v_exp_f32_e32 v133, v133
	v_cvt_pk_bf16_f32 v136, v169, v170
	v_cvt_pk_bf16_f32 v137, v144, v145
	v_lshl_add_u64 v[138:139], v[138:139], 0, v[130:131]
	v_add_f32_e32 v133, 1.0, v133
	global_store_dwordx4 v[138:139], v[134:137], off offset:-4096 nt
	v_mul_f32_e32 v138, 0xbfb8aa3b, v24
	v_mul_f32_e32 v139, 0xbfb8aa3b, v25
	v_pk_add_f32 v[134:135], v[140:141], 1.0 op_sel_hi:[1,0]
	v_rcp_f32_e32 v140, v133
	v_mul_f32_e32 v133, 0xbfb8aa3b, v33
	v_min_f32_e32 v133, 0x42700000, v133
	v_exp_f32_e32 v133, v133
	v_min_f32_e32 v138, 0x42700000, v138
	v_min_f32_e32 v139, 0x42700000, v139
	v_exp_f32_e32 v138, v138
	v_exp_f32_e32 v139, v139
	v_add_f32_e32 v133, 1.0, v133
	v_rcp_f32_e32 v141, v133
	v_pk_mul_f32 v[136:137], v[142:143], v[134:135]
; __device__ __forceinline__ unsigned long long rt() { return __builtin_amdgcn_s_memrealtime(); }
; __device__ __forceinline__ u32x4 pack8f(const f32x4 a, const f32x4 b) { u32x4 w; w.x = cvt_pk_bf16(a[0], a[1]); w.y = cvt_pk_bf16(a[2], a[3]); w.z = cvt_pk_bf16(b[0], b[1]); w.w = cvt_pk_bf16(b[2], b[3]); return w; }
;     __device__ __forceinline__ void operator()(f32x4 (&acc)[2][2][4][2], const Unit& u, int wr, int wc, int fr, int fq) const {
;     ...
;                     f32x4 rt[2], s1[2];
; #pragma unroll
;                     for (int n = 0; n < 2; ++n)
; #pragma unroll
;                         for (int i = 0; i < 4; ++i) {
;                             const float e0 = __builtin_amdgcn_exp2f(fminf(-1.4426950408889634f * acc[ai][0][m][n][i], 60.f)), e1 = __builtin_amdgcn_exp2f(fminf(-1.4426950408889634f * acc[ai][1][m][n][i], 60.f));
;                             rt[n][i] = (1.f + e1) * __builtin_amdgcn_rcpf(1.f + e0); s1[n][i] = __builtin_amdgcn_rcpf(1.f + e1); }
;                     __builtin_nontemporal_store(pack8f(rt[0], rt[1]), (u32x4*)(RT + (size_t)(u.pm * 256 + rl) * DM + j0));
;                     __builtin_nontemporal_store(pack8f(s1[0], s1[1]), (u32x4*)(G1 + (size_t)(u.pm * 256 + rl) * DM + j0));
	v_rcp_f32_e32 v133, v134
	v_rcp_f32_e32 v154, v135
	v_pk_add_f32 v[134:135], v[138:139], 1.0 op_sel_hi:[1,0]
	s_nop 0
	v_pk_mul_f32 v[138:139], v[140:141], v[134:135]
	v_mul_f32_e32 v140, 0xbfb8aa3b, v26
	v_min_f32_e32 v140, 0x42700000, v140
	v_exp_f32_e32 v141, v140
	v_mul_f32_e32 v140, 0xbfb8aa3b, v18
	v_min_f32_e32 v140, 0x42700000, v140
	v_exp_f32_e32 v140, v140
	v_add_f32_e32 v141, 1.0, v141
	v_rcp_f32_e32 v142, v141
	v_mul_f32_e32 v141, 0xbfb8aa3b, v27
	v_min_f32_e32 v141, 0x42700000, v141
	v_exp_f32_e32 v143, v141
	v_mul_f32_e32 v141, 0xbfb8aa3b, v19
	v_min_f32_e32 v141, 0x42700000, v141
	v_exp_f32_e32 v141, v141
	v_add_f32_e32 v143, 1.0, v143
	v_rcp_f32_e32 v143, v143
	v_rcp_f32_e32 v167, v134
	v_rcp_f32_e32 v168, v135
	v_pk_add_f32 v[134:135], v[140:141], 1.0 op_sel_hi:[1,0]
	s_nop 0
	v_pk_mul_f32 v[140:141], v[142:143], v[134:135]
	v_mul_f32_e32 v142, 0xbfb8aa3b, v28
	v_min_f32_e32 v142, 0x42700000, v142
	v_exp_f32_e32 v143, v142
	v_mul_f32_e32 v142, 0xbfb8aa3b, v20
	v_min_f32_e32 v142, 0x42700000, v142
	v_exp_f32_e32 v142, v142
	v_add_f32_e32 v143, 1.0, v143
	v_rcp_f32_e32 v144, v143
	v_mul_f32_e32 v143, 0xbfb8aa3b, v29
	v_min_f32_e32 v143, 0x42700000, v143
	v_exp_f32_e32 v145, v143
	v_mul_f32_e32 v143, 0xbfb8aa3b, v21
	v_min_f32_e32 v143, 0x42700000, v143
	v_exp_f32_e32 v143, v143
	v_add_f32_e32 v145, 1.0, v145
	v_rcp_f32_e32 v145, v145
	v_rcp_f32_e32 v169, v134
	v_rcp_f32_e32 v170, v135
	v_pk_add_f32 v[134:135], v[142:143], 1.0 op_sel_hi:[1,0]
	s_nop 0
	v_pk_mul_f32 v[142:143], v[144:145], v[134:135]
	v_rcp_f32_e32 v145, v135
	v_cvt_pk_bf16_f32 v135, v138, v139
	v_add_u32_e32 v138, 0xa0, v132
	v_ashrrev_i32_e32 v139, 31, v138
	v_lshlrev_b64 v[138:139], 11, v[138:139]
	v_rcp_f32_e32 v144, v134
	v_cvt_pk_bf16_f32 v134, v136, v137
	v_cvt_pk_bf16_f32 v136, v140, v141
	v_lshl_add_u64 v[140:141], s[68:69], 0, v[138:139]
	v_cvt_pk_bf16_f32 v137, v142, v143
	v_lshl_add_u64 v[140:141], v[140:141], 0, v[130:131]
	global_store_dwordx4 v[140:141], v[134:137], off offset:-4096 nt
	v_mul_f32_e32 v140, 0xbfb8aa3b, v6
	v_mul_f32_e32 v141, 0xbfb8aa3b, v7
	v_cvt_pk_bf16_f32 v134, v133, v154
	v_mul_f32_e32 v133, 0xbfb8aa3b, v14
	v_min_f32_e32 v133, 0x42700000, v133
	v_exp_f32_e32 v133, v133
	v_min_f32_e32 v140, 0x42700000, v140
	v_min_f32_e32 v141, 0x42700000, v141
	v_exp_f32_e32 v140, v140
	v_add_f32_e32 v133, 1.0, v133
	v_rcp_f32_e32 v142, v133
	v_mul_f32_e32 v133, 0xbfb8aa3b, v15
	v_min_f32_e32 v133, 0x42700000, v133
	v_exp_f32_e32 v133, v133
	v_exp_f32_e32 v141, v141
	v_lshl_add_u64 v[138:139], s[70:71], 0, v[138:139]
	v_cvt_pk_bf16_f32 v135, v167, v168
	v_add_f32_e32 v133, 1.0, v133
	v_rcp_f32_e32 v143, v133
	v_mul_f32_e32 v133, 0xbfb8aa3b, v16
	v_min_f32_e32 v133, 0x42700000, v133
	v_exp_f32_e32 v133, v133
	v_cvt_pk_bf16_f32 v136, v169, v170
	v_cvt_pk_bf16_f32 v137, v144, v145
	v_lshl_add_u64 v[138:139], v[138:139], 0, v[130:131]
	v_add_f32_e32 v133, 1.0, v133
	global_store_dwordx4 v[138:139], v[134:137], off offset:-4096 nt
	v_mul_f32_e32 v138, 0xbfb8aa3b, v8
	v_mul_f32_e32 v139, 0xbfb8aa3b, v9
	v_pk_add_f32 v[134:135], v[140:141], 1.0 op_sel_hi:[1,0]
	v_rcp_f32_e32 v140, v133
	v_mul_f32_e32 v133, 0xbfb8aa3b, v17
	v_min_f32_e32 v133, 0x42700000, v133
	v_exp_f32_e32 v133, v133
	v_pk_mul_f32 v[136:137], v[142:143], v[134:135]
	v_min_f32_e32 v138, 0x42700000, v138
	v_min_f32_e32 v139, 0x42700000, v139
	v_add_f32_e32 v133, 1.0, v133
	v_rcp_f32_e32 v141, v133
	v_mul_f32_e32 v133, 0xbfb8aa3b, v10
	v_min_f32_e32 v133, 0x42700000, v133
	v_exp_f32_e32 v133, v133
	v_exp_f32_e32 v138, v138
	v_exp_f32_e32 v139, v139
	v_rcp_f32_e32 v154, v134
	v_add_f32_e32 v133, 1.0, v133
	v_rcp_f32_e32 v142, v133
	v_mul_f32_e32 v133, 0xbfb8aa3b, v11
	v_min_f32_e32 v133, 0x42700000, v133
	v_exp_f32_e32 v133, v133
	v_rcp_f32_e32 v167, v135
	v_pk_add_f32 v[134:135], v[138:139], 1.0 op_sel_hi:[1,0]
	v_add_u32_e32 v132, 0xb0, v132
	v_add_f32_e32 v133, 1.0, v133
	v_rcp_f32_e32 v143, v133
	v_mul_f32_e32 v133, 0xbfb8aa3b, v12
	v_min_f32_e32 v133, 0x42700000, v133
	v_exp_f32_e32 v133, v133
	v_pk_mul_f32 v[138:139], v[140:141], v[134:135]
	v_mul_f32_e32 v140, 0xbfb8aa3b, v2
	v_mul_f32_e32 v141, 0xbfb8aa3b, v3
	v_min_f32_e32 v140, 0x42700000, v140
	v_min_f32_e32 v141, 0x42700000, v141
	v_exp_f32_e32 v140, v140
	v_exp_f32_e32 v141, v141
	v_add_f32_e32 v133, 1.0, v133
	v_rcp_f32_e32 v144, v133
	v_mul_f32_e32 v133, 0xbfb8aa3b, v13
	v_min_f32_e32 v133, 0x42700000, v133
	v_exp_f32_e32 v133, v133
	v_rcp_f32_e32 v168, v134
	v_rcp_f32_e32 v169, v135
	v_pk_add_f32 v[134:135], v[140:141], 1.0 op_sel_hi:[1,0]
	v_add_f32_e32 v133, 1.0, v133
	v_pk_mul_f32 v[140:141], v[142:143], v[134:135]
	v_mul_f32_e32 v142, 0xbfb8aa3b, v4
	v_mul_f32_e32 v143, 0xbfb8aa3b, v5
	v_min_f32_e32 v142, 0x42700000, v142
	v_min_f32_e32 v143, 0x42700000, v143
	v_exp_f32_e32 v142, v142
	v_exp_f32_e32 v143, v143
	v_rcp_f32_e32 v145, v133
	v_rcp_f32_e32 v170, v134
	v_rcp_f32_e32 v171, v135
	v_pk_add_f32 v[134:135], v[142:143], 1.0 op_sel_hi:[1,0]
	v_ashrrev_i32_e32 v133, 31, v132
	v_pk_mul_f32 v[142:143], v[144:145], v[134:135]
	v_rcp_f32_e32 v144, v134
	v_rcp_f32_e32 v145, v135
	v_cvt_pk_bf16_f32 v135, v138, v139
	v_lshlrev_b64 v[138:139], 11, v[132:133]
	v_lshl_add_u64 v[132:133], s[68:69], 0, v[138:139]
	v_cvt_pk_bf16_f32 v134, v136, v137
	v_cvt_pk_bf16_f32 v136, v140, v141
	v_cvt_pk_bf16_f32 v137, v142, v143
	v_lshl_add_u64 v[132:133], v[132:133], 0, v[130:131]
	global_store_dwordx4 v[132:133], v[134:137], off offset:-4096 nt
	v_cvt_pk_bf16_f32 v132, v154, v167
	v_cvt_pk_bf16_f32 v133, v168, v169
	v_lshl_add_u64 v[136:137], s[70:71], 0, v[138:139]
	v_cvt_pk_bf16_f32 v134, v170, v171
	v_cvt_pk_bf16_f32 v135, v144, v145
	v_lshl_add_u64 v[130:131], v[136:137], 0, v[130:131]
	global_store_dwordx4 v[130:131], v[132:135], off offset:-4096 nt
	s_branch .LBB0_239

; __device__ __forceinline__ float fast_silu(float v) { return v * fast_sigmoid(v); }
; __device__ __forceinline__ u32x4 pack8f(const f32x4 a, const f32x4 b) { u32x4 w; w.x = cvt_pk_bf16(a[0], a[1]); w.y = cvt_pk_bf16(a[2], a[3]); w.z = cvt_pk_bf16(b[0], b[1]); w.w = cvt_pk_bf16(b[2], b[3]); return w; }
;     __device__ __forceinline__ void operator()(f32x4 (&acc)[2][2][4][2], const Unit& u, int wr, int wc, int fr, int fq) const {
;     ...
;         } else if (pn < 8) {
; #pragma unroll
;             for (int ai = 0; ai < 2; ++ai)
; #pragma unroll
;                 for (int m = 0; m < 4; ++m) { const int rl = rl0 + 128 * ai + 16 * m;
; #pragma unroll
;                     for (int bj = 0; bj < 2; ++bj) { f32x4 a = acc[ai][bj][m][0], c = acc[ai][bj][m][1];
; #pragma unroll
;                         for (int i = 0; i < 4; ++i) { a[i] = fast_silu(a[i]); c[i] = fast_silu(c[i]); }
;                         *(u32x4*)(SG + (size_t)(u.pm * 256 + rl) * AW + (pn - 6) * 256 + 128 * bj + 32 * wc + 8 * fq) = pack8f(a, c); }
;                 }
.LBB0_168:
	s_andn2_b64 vcc, exec, s[88:89]
	s_cbranch_vccnz .LBB0_170
	v_mul_f32_e32 v131, 0xbfb8aa3b, v122
	v_mul_f32_e32 v134, 0xbfb8aa3b, v127
	v_exp_f32_e32 v131, v131
	v_exp_f32_e32 v135, v134
	v_mul_f32_e32 v134, 0xbfb8aa3b, v123
	v_exp_f32_e32 v136, v134
	v_mul_f32_e32 v130, 0xbfb8aa3b, v126
	v_exp_f32_e32 v130, v130
	v_add_f32_e32 v131, 1.0, v131
	v_mul_f32_e32 v137, 0xbfb8aa3b, v124
	v_mul_f32_e32 v138, 0xbfb8aa3b, v129
	v_rcp_f32_e32 v134, v131
	v_add_f32_e32 v131, 1.0, v135
	v_add_f32_e32 v135, 1.0, v136
	v_mul_f32_e32 v136, 0xbfb8aa3b, v128
	v_exp_f32_e32 v137, v137
	v_exp_f32_e32 v139, v138
	v_mul_f32_e32 v138, 0xbfb8aa3b, v125
	v_exp_f32_e32 v136, v136
	v_exp_f32_e32 v140, v138
	v_add_f32_e32 v130, 1.0, v130
	v_rcp_f32_e32 v130, v130
	v_rcp_f32_e32 v131, v131
	v_add_f32_e32 v137, 1.0, v137
	v_rcp_f32_e32 v135, v135
	v_add_f32_e32 v136, 1.0, v136
	v_rcp_f32_e32 v138, v137
	v_add_f32_e32 v137, 1.0, v139
	v_add_f32_e32 v139, 1.0, v140
	v_rcp_f32_e32 v136, v136
	v_rcp_f32_e32 v137, v137
	v_rcp_f32_e32 v139, v139
	v_pk_mul_f32 v[130:131], v[126:127], v[130:131]
	v_pk_mul_f32 v[140:141], v[122:123], v[134:135]
	v_cvt_pk_bf16_f32 v134, v130, v131
	v_add_u32_e32 v130, s1, v166
	v_pk_mul_f32 v[136:137], v[128:129], v[136:137]
	v_pk_mul_f32 v[138:139], v[124:125], v[138:139]
	v_ashrrev_i32_e32 v131, 31, v130
	v_cvt_pk_bf16_f32 v135, v136, v137
	v_cvt_pk_bf16_f32 v137, v138, v139
	v_lshlrev_b64 v[138:139], 10, v[130:131]
	v_lshlrev_b32_e32 v132, 3, v200
	v_lshl_add_u64 v[138:139], s[62:63], 0, v[138:139]
	s_lshl_b32 s22, s10, 9
	v_ashrrev_i32_e32 v133, 31, v132
	v_lshl_add_u64 v[138:139], v[138:139], 0, s[22:23]
	s_mov_b32 s79, s23
	v_lshl_add_u64 v[138:139], v[138:139], 0, s[78:79]
	v_lshlrev_b64 v[132:133], 1, v[132:133]
	v_mul_f32_e32 v131, 0xbfb8aa3b, v118
	v_cvt_pk_bf16_f32 v136, v140, v141
	v_lshl_add_u64 v[138:139], v[138:139], 0, v[132:133]
	v_exp_f32_e32 v131, v131
	v_mul_f32_e32 v140, 0xbfb8aa3b, v114
	v_exp_f32_e32 v140, v140
	global_store_dwordx4 v[138:139], v[134:137], off offset:-3072
	v_add_f32_e32 v131, 1.0, v131
	v_mul_f32_e32 v142, 0xbfb8aa3b, v117
	v_mul_f32_e32 v135, 0xbfb8aa3b, v119
	v_exp_f32_e32 v135, v135
	v_mul_f32_e32 v136, 0xbfb8aa3b, v115
	v_exp_f32_e32 v137, v136
	v_rcp_f32_e32 v134, v131
	v_add_f32_e32 v131, 1.0, v140
	v_rcp_f32_e32 v136, v131
	v_add_f32_e32 v131, 1.0, v135
	v_rcp_f32_e32 v135, v131
	v_add_f32_e32 v131, 1.0, v137
	v_mul_f32_e32 v137, 0xbfb8aa3b, v120
	v_exp_f32_e32 v140, v137
	v_mul_f32_e32 v137, 0xbfb8aa3b, v116
	v_exp_f32_e32 v141, v137
	v_rcp_f32_e32 v137, v131
	v_add_f32_e32 v131, 1.0, v140
	v_rcp_f32_e32 v140, v131
	v_add_f32_e32 v131, 1.0, v141
	v_mul_f32_e32 v141, 0xbfb8aa3b, v121
	v_exp_f32_e32 v141, v141
	v_exp_f32_e32 v143, v142
	v_rcp_f32_e32 v142, v131
	v_pk_mul_f32 v[134:135], v[118:119], v[134:135]
	v_add_f32_e32 v131, 1.0, v141
	v_rcp_f32_e32 v141, v131
	v_add_f32_e32 v131, 1.0, v143
	v_rcp_f32_e32 v143, v131
	v_pk_mul_f32 v[136:137], v[114:115], v[136:137]
	v_pk_mul_f32 v[140:141], v[120:121], v[140:141]
	v_mul_f32_e32 v131, 0xbfb8aa3b, v110
	v_pk_mul_f32 v[142:143], v[116:117], v[142:143]
	v_cvt_pk_bf16_f32 v134, v134, v135
	v_cvt_pk_bf16_f32 v135, v140, v141
	v_cvt_pk_bf16_f32 v136, v136, v137
	v_cvt_pk_bf16_f32 v137, v142, v143
	v_exp_f32_e32 v131, v131
	v_mul_f32_e32 v140, 0xbfb8aa3b, v106
	v_exp_f32_e32 v140, v140
	global_store_dwordx4 v[138:139], v[134:137], off offset:-2816
	v_add_f32_e32 v131, 1.0, v131
	v_mul_f32_e32 v142, 0xbfb8aa3b, v101
	v_mul_f32_e32 v135, 0xbfb8aa3b, v111
	v_exp_f32_e32 v135, v135
	v_mul_f32_e32 v136, 0xbfb8aa3b, v107
	v_exp_f32_e32 v137, v136
	v_rcp_f32_e32 v134, v131
	v_add_f32_e32 v131, 1.0, v140
	v_rcp_f32_e32 v136, v131
	v_add_f32_e32 v131, 1.0, v135
	v_rcp_f32_e32 v135, v131
	v_add_f32_e32 v131, 1.0, v137
	v_mul_f32_e32 v137, 0xbfb8aa3b, v112
	v_exp_f32_e32 v138, v137
	v_mul_f32_e32 v137, 0xbfb8aa3b, v108
	v_exp_f32_e32 v139, v137
	v_rcp_f32_e32 v137, v131
	v_add_f32_e32 v131, 1.0, v138
	v_rcp_f32_e32 v138, v131
	v_add_f32_e32 v131, 1.0, v139
	v_mul_f32_e32 v139, 0xbfb8aa3b, v113
	v_exp_f32_e32 v139, v139
	v_mul_f32_e32 v140, 0xbfb8aa3b, v109
	v_exp_f32_e32 v141, v140
	v_rcp_f32_e32 v140, v131
	v_add_f32_e32 v131, 1.0, v139
	v_rcp_f32_e32 v139, v131
	v_pk_mul_f32 v[134:135], v[110:111], v[134:135]
	v_add_f32_e32 v131, 1.0, v141
	v_cvt_pk_bf16_f32 v134, v134, v135
	v_pk_mul_f32 v[138:139], v[112:113], v[138:139]
	v_rcp_f32_e32 v141, v131
	v_cvt_pk_bf16_f32 v135, v138, v139
	v_add_u32_e32 v138, 16, v130
	v_ashrrev_i32_e32 v139, 31, v138
	v_lshlrev_b64 v[138:139], 10, v[138:139]
	v_lshl_add_u64 v[138:139], s[62:63], 0, v[138:139]
	v_lshl_add_u64 v[138:139], v[138:139], 0, s[22:23]
	v_pk_mul_f32 v[136:137], v[106:107], v[136:137]
	v_pk_mul_f32 v[140:141], v[108:109], v[140:141]
	v_lshl_add_u64 v[138:139], v[138:139], 0, s[78:79]
	v_mul_f32_e32 v131, 0xbfb8aa3b, v102
	v_cvt_pk_bf16_f32 v136, v136, v137
	v_cvt_pk_bf16_f32 v137, v140, v141
	v_lshl_add_u64 v[138:139], v[138:139], 0, v[132:133]
	v_exp_f32_e32 v131, v131
	v_mul_f32_e32 v140, 0xbfb8aa3b, v98
	v_exp_f32_e32 v140, v140
	global_store_dwordx4 v[138:139], v[134:137], off offset:-3072
	v_add_f32_e32 v131, 1.0, v131
	v_exp_f32_e32 v143, v142
	v_mul_f32_e32 v135, 0xbfb8aa3b, v103
	v_exp_f32_e32 v135, v135
	v_mul_f32_e32 v136, 0xbfb8aa3b, v99
	v_exp_f32_e32 v137, v136
	v_rcp_f32_e32 v134, v131
	v_add_f32_e32 v131, 1.0, v140
	v_rcp_f32_e32 v136, v131
	v_add_f32_e32 v131, 1.0, v135
	v_rcp_f32_e32 v135, v131
	v_add_f32_e32 v131, 1.0, v137
	v_mul_f32_e32 v137, 0xbfb8aa3b, v104
	v_exp_f32_e32 v140, v137
	v_mul_f32_e32 v137, 0xbfb8aa3b, v100
	v_exp_f32_e32 v141, v137
	v_rcp_f32_e32 v137, v131
; __device__ __forceinline__ float fast_silu(float v) { return v * fast_sigmoid(v); }
; __device__ __forceinline__ u32x4 pack8f(const f32x4 a, const f32x4 b) { u32x4 w; w.x = cvt_pk_bf16(a[0], a[1]); w.y = cvt_pk_bf16(a[2], a[3]); w.z = cvt_pk_bf16(b[0], b[1]); w.w = cvt_pk_bf16(b[2], b[3]); return w; }
;     __device__ __forceinline__ void operator()(f32x4 (&acc)[2][2][4][2], const Unit& u, int wr, int wc, int fr, int fq) const {
;     ...
;                 for (int m = 0; m < 4; ++m) { const int rl = rl0 + 128 * ai + 16 * m;
; #pragma unroll
;                     for (int bj = 0; bj < 2; ++bj) { f32x4 a = acc[ai][bj][m][0], c = acc[ai][bj][m][1];
; #pragma unroll
;                         for (int i = 0; i < 4; ++i) { a[i] = fast_silu(a[i]); c[i] = fast_silu(c[i]); }
;                         *(u32x4*)(SG + (size_t)(u.pm * 256 + rl) * AW + (pn - 6) * 256 + 128 * bj + 32 * wc + 8 * fq) = pack8f(a, c); }
	v_add_f32_e32 v131, 1.0, v140
	v_rcp_f32_e32 v140, v131
	v_add_f32_e32 v131, 1.0, v141
	v_mul_f32_e32 v141, 0xbfb8aa3b, v105
	v_exp_f32_e32 v141, v141
	v_rcp_f32_e32 v142, v131
	v_pk_mul_f32 v[134:135], v[102:103], v[134:135]
	v_pk_mul_f32 v[136:137], v[98:99], v[136:137]
	v_add_f32_e32 v131, 1.0, v141
	v_rcp_f32_e32 v141, v131
	v_add_f32_e32 v131, 1.0, v143
	v_rcp_f32_e32 v143, v131
	v_mul_f32_e32 v131, 0xbfb8aa3b, v94
	v_pk_mul_f32 v[140:141], v[104:105], v[140:141]
	v_cvt_pk_bf16_f32 v134, v134, v135
	v_pk_mul_f32 v[142:143], v[100:101], v[142:143]
	v_cvt_pk_bf16_f32 v135, v140, v141
	v_cvt_pk_bf16_f32 v136, v136, v137
	v_cvt_pk_bf16_f32 v137, v142, v143
	v_exp_f32_e32 v131, v131
	v_mul_f32_e32 v140, 0xbfb8aa3b, v90
	v_exp_f32_e32 v140, v140
	global_store_dwordx4 v[138:139], v[134:137], off offset:-2816
	v_add_f32_e32 v131, 1.0, v131
	v_mul_f32_e32 v142, 0xbfb8aa3b, v85
	v_mul_f32_e32 v135, 0xbfb8aa3b, v95
	v_exp_f32_e32 v135, v135
	v_mul_f32_e32 v136, 0xbfb8aa3b, v91
	v_exp_f32_e32 v137, v136
	v_rcp_f32_e32 v134, v131
	v_add_f32_e32 v131, 1.0, v140
	v_rcp_f32_e32 v136, v131
	v_add_f32_e32 v131, 1.0, v135
	v_rcp_f32_e32 v135, v131
	v_add_f32_e32 v131, 1.0, v137
	v_mul_f32_e32 v137, 0xbfb8aa3b, v96
	v_exp_f32_e32 v138, v137
	v_mul_f32_e32 v137, 0xbfb8aa3b, v92
	v_exp_f32_e32 v139, v137
	v_rcp_f32_e32 v137, v131
	v_add_f32_e32 v131, 1.0, v138
	v_rcp_f32_e32 v138, v131
	v_add_f32_e32 v131, 1.0, v139
	v_mul_f32_e32 v139, 0xbfb8aa3b, v97
	v_exp_f32_e32 v139, v139
	v_mul_f32_e32 v140, 0xbfb8aa3b, v93
	v_exp_f32_e32 v141, v140
	v_rcp_f32_e32 v140, v131
	v_add_f32_e32 v131, 1.0, v139
	v_rcp_f32_e32 v139, v131
	v_pk_mul_f32 v[134:135], v[94:95], v[134:135]
	v_add_f32_e32 v131, 1.0, v141
	v_cvt_pk_bf16_f32 v134, v134, v135
	v_pk_mul_f32 v[138:139], v[96:97], v[138:139]
	v_rcp_f32_e32 v141, v131
	v_cvt_pk_bf16_f32 v135, v138, v139
	v_add_u32_e32 v138, 32, v130
	v_ashrrev_i32_e32 v139, 31, v138
	v_lshlrev_b64 v[138:139], 10, v[138:139]
	v_lshl_add_u64 v[138:139], s[62:63], 0, v[138:139]
	v_lshl_add_u64 v[138:139], v[138:139], 0, s[22:23]
	v_pk_mul_f32 v[136:137], v[90:91], v[136:137]
	v_pk_mul_f32 v[140:141], v[92:93], v[140:141]
	v_lshl_add_u64 v[138:139], v[138:139], 0, s[78:79]
	v_mul_f32_e32 v131, 0xbfb8aa3b, v86
	v_cvt_pk_bf16_f32 v136, v136, v137
	v_cvt_pk_bf16_f32 v137, v140, v141
	v_lshl_add_u64 v[138:139], v[138:139], 0, v[132:133]
	v_exp_f32_e32 v131, v131
	v_mul_f32_e32 v140, 0xbfb8aa3b, v82
	v_exp_f32_e32 v140, v140
	global_store_dwordx4 v[138:139], v[134:137], off offset:-3072
	v_add_f32_e32 v131, 1.0, v131
	v_exp_f32_e32 v143, v142
	v_mul_f32_e32 v135, 0xbfb8aa3b, v87
	v_exp_f32_e32 v135, v135
	v_mul_f32_e32 v136, 0xbfb8aa3b, v83
	v_exp_f32_e32 v137, v136
	v_rcp_f32_e32 v134, v131
	v_add_f32_e32 v131, 1.0, v140
	v_rcp_f32_e32 v136, v131
	v_add_f32_e32 v131, 1.0, v135
	v_rcp_f32_e32 v135, v131
	v_add_f32_e32 v131, 1.0, v137
	v_mul_f32_e32 v137, 0xbfb8aa3b, v88
	v_exp_f32_e32 v140, v137
	v_mul_f32_e32 v137, 0xbfb8aa3b, v84
	v_exp_f32_e32 v141, v137
	v_rcp_f32_e32 v137, v131
	v_add_f32_e32 v131, 1.0, v140
	v_rcp_f32_e32 v140, v131
	v_add_f32_e32 v131, 1.0, v141
	v_mul_f32_e32 v141, 0xbfb8aa3b, v89
	v_exp_f32_e32 v141, v141
	v_rcp_f32_e32 v142, v131
	v_pk_mul_f32 v[134:135], v[86:87], v[134:135]
	v_pk_mul_f32 v[136:137], v[82:83], v[136:137]
	v_add_f32_e32 v131, 1.0, v141
	v_rcp_f32_e32 v141, v131
	v_add_f32_e32 v131, 1.0, v143
	v_rcp_f32_e32 v143, v131
	v_mul_f32_e32 v131, 0xbfb8aa3b, v78
	v_pk_mul_f32 v[140:141], v[88:89], v[140:141]
	v_cvt_pk_bf16_f32 v134, v134, v135
	v_pk_mul_f32 v[142:143], v[84:85], v[142:143]
	v_cvt_pk_bf16_f32 v135, v140, v141
	v_cvt_pk_bf16_f32 v136, v136, v137
	v_cvt_pk_bf16_f32 v137, v142, v143
	v_exp_f32_e32 v131, v131
	v_mul_f32_e32 v140, 0xbfb8aa3b, v74
	v_exp_f32_e32 v140, v140
	global_store_dwordx4 v[138:139], v[134:137], off offset:-2816
	v_add_f32_e32 v131, 1.0, v131
	v_mul_f32_e32 v142, 0xbfb8aa3b, v69
	v_mul_f32_e32 v135, 0xbfb8aa3b, v79
	v_exp_f32_e32 v135, v135
	v_mul_f32_e32 v136, 0xbfb8aa3b, v75
	v_exp_f32_e32 v137, v136
	v_rcp_f32_e32 v134, v131
	v_add_f32_e32 v131, 1.0, v140
	v_rcp_f32_e32 v136, v131
	v_add_f32_e32 v131, 1.0, v135
	v_rcp_f32_e32 v135, v131
	v_add_f32_e32 v131, 1.0, v137
	v_mul_f32_e32 v137, 0xbfb8aa3b, v80
	v_exp_f32_e32 v138, v137
	v_mul_f32_e32 v137, 0xbfb8aa3b, v76
	v_exp_f32_e32 v139, v137
	v_rcp_f32_e32 v137, v131
	v_add_f32_e32 v131, 1.0, v138
	v_rcp_f32_e32 v138, v131
	v_add_f32_e32 v131, 1.0, v139
	v_mul_f32_e32 v139, 0xbfb8aa3b, v81
	v_exp_f32_e32 v139, v139
	v_mul_f32_e32 v140, 0xbfb8aa3b, v77
	v_exp_f32_e32 v141, v140
	v_rcp_f32_e32 v140, v131
	v_add_f32_e32 v131, 1.0, v139
	v_rcp_f32_e32 v139, v131
	v_pk_mul_f32 v[134:135], v[78:79], v[134:135]
	v_add_f32_e32 v131, 1.0, v141
	v_cvt_pk_bf16_f32 v134, v134, v135
	v_pk_mul_f32 v[138:139], v[80:81], v[138:139]
	v_rcp_f32_e32 v141, v131
	v_cvt_pk_bf16_f32 v135, v138, v139
	v_add_u32_e32 v138, 48, v130
	v_ashrrev_i32_e32 v139, 31, v138
	v_lshlrev_b64 v[138:139], 10, v[138:139]
	v_lshl_add_u64 v[138:139], s[62:63], 0, v[138:139]
	v_lshl_add_u64 v[138:139], v[138:139], 0, s[22:23]
	v_pk_mul_f32 v[136:137], v[74:75], v[136:137]
	v_pk_mul_f32 v[140:141], v[76:77], v[140:141]
	v_lshl_add_u64 v[138:139], v[138:139], 0, s[78:79]
	v_mul_f32_e32 v131, 0xbfb8aa3b, v70
	v_cvt_pk_bf16_f32 v136, v136, v137
	v_cvt_pk_bf16_f32 v137, v140, v141
	v_lshl_add_u64 v[138:139], v[138:139], 0, v[132:133]
	v_exp_f32_e32 v131, v131
	v_mul_f32_e32 v140, 0xbfb8aa3b, v66
	v_exp_f32_e32 v140, v140
	global_store_dwordx4 v[138:139], v[134:137], off offset:-3072
	v_add_f32_e32 v131, 1.0, v131
	v_exp_f32_e32 v143, v142
	v_mul_f32_e32 v135, 0xbfb8aa3b, v71
; __device__ __forceinline__ float fast_silu(float v) { return v * fast_sigmoid(v); }
; __device__ __forceinline__ u32x4 pack8f(const f32x4 a, const f32x4 b) { u32x4 w; w.x = cvt_pk_bf16(a[0], a[1]); w.y = cvt_pk_bf16(a[2], a[3]); w.z = cvt_pk_bf16(b[0], b[1]); w.w = cvt_pk_bf16(b[2], b[3]); return w; }
;     __device__ __forceinline__ void operator()(f32x4 (&acc)[2][2][4][2], const Unit& u, int wr, int wc, int fr, int fq) const {
;     ...
;                 for (int m = 0; m < 4; ++m) { const int rl = rl0 + 128 * ai + 16 * m;
; #pragma unroll
;                     for (int bj = 0; bj < 2; ++bj) { f32x4 a = acc[ai][bj][m][0], c = acc[ai][bj][m][1];
; #pragma unroll
;                         for (int i = 0; i < 4; ++i) { a[i] = fast_silu(a[i]); c[i] = fast_silu(c[i]); }
;                         *(u32x4*)(SG + (size_t)(u.pm * 256 + rl) * AW + (pn - 6) * 256 + 128 * bj + 32 * wc + 8 * fq) = pack8f(a, c); }
	v_exp_f32_e32 v135, v135
	v_mul_f32_e32 v136, 0xbfb8aa3b, v67
	v_exp_f32_e32 v137, v136
	v_rcp_f32_e32 v134, v131
	v_add_f32_e32 v131, 1.0, v140
	v_rcp_f32_e32 v136, v131
	v_add_f32_e32 v131, 1.0, v135
	v_rcp_f32_e32 v135, v131
	v_add_f32_e32 v131, 1.0, v137
	v_mul_f32_e32 v137, 0xbfb8aa3b, v72
	v_exp_f32_e32 v140, v137
	v_mul_f32_e32 v137, 0xbfb8aa3b, v68
	v_exp_f32_e32 v141, v137
	v_rcp_f32_e32 v137, v131
	v_add_f32_e32 v131, 1.0, v140
	v_rcp_f32_e32 v140, v131
	v_add_f32_e32 v131, 1.0, v141
	v_mul_f32_e32 v141, 0xbfb8aa3b, v73
	v_exp_f32_e32 v141, v141
	v_rcp_f32_e32 v142, v131
	v_pk_mul_f32 v[134:135], v[70:71], v[134:135]
	v_pk_mul_f32 v[136:137], v[66:67], v[136:137]
	v_add_f32_e32 v131, 1.0, v141
	v_rcp_f32_e32 v141, v131
	v_add_f32_e32 v131, 1.0, v143
	v_rcp_f32_e32 v143, v131
	v_mul_f32_e32 v131, 0xbfb8aa3b, v62
	v_pk_mul_f32 v[140:141], v[72:73], v[140:141]
	v_cvt_pk_bf16_f32 v134, v134, v135
	v_pk_mul_f32 v[142:143], v[68:69], v[142:143]
	v_cvt_pk_bf16_f32 v135, v140, v141
	v_cvt_pk_bf16_f32 v136, v136, v137
	v_cvt_pk_bf16_f32 v137, v142, v143
	v_exp_f32_e32 v131, v131
	v_mul_f32_e32 v140, 0xbfb8aa3b, v58
	v_exp_f32_e32 v140, v140
	global_store_dwordx4 v[138:139], v[134:137], off offset:-2816
	v_add_f32_e32 v131, 1.0, v131
	v_mul_f32_e32 v142, 0xbfb8aa3b, v53
	v_mul_f32_e32 v135, 0xbfb8aa3b, v63
	v_exp_f32_e32 v135, v135
	v_mul_f32_e32 v136, 0xbfb8aa3b, v59
	v_exp_f32_e32 v137, v136
	v_rcp_f32_e32 v134, v131
	v_add_f32_e32 v131, 1.0, v140
	v_rcp_f32_e32 v136, v131
	v_add_f32_e32 v131, 1.0, v135
	v_rcp_f32_e32 v135, v131
	v_add_f32_e32 v131, 1.0, v137
	v_mul_f32_e32 v137, 0xbfb8aa3b, v64
	v_exp_f32_e32 v138, v137
	v_mul_f32_e32 v137, 0xbfb8aa3b, v60
	v_exp_f32_e32 v139, v137
	v_rcp_f32_e32 v137, v131
	v_add_f32_e32 v131, 1.0, v138
	v_rcp_f32_e32 v138, v131
	v_add_f32_e32 v131, 1.0, v139
	v_mul_f32_e32 v139, 0xbfb8aa3b, v65
	v_exp_f32_e32 v139, v139
	v_mul_f32_e32 v140, 0xbfb8aa3b, v61
	v_exp_f32_e32 v141, v140
	v_rcp_f32_e32 v140, v131
	v_add_f32_e32 v131, 1.0, v139
	v_rcp_f32_e32 v139, v131
	v_pk_mul_f32 v[134:135], v[62:63], v[134:135]
	v_add_f32_e32 v131, 1.0, v141
	v_cvt_pk_bf16_f32 v134, v134, v135
	v_pk_mul_f32 v[138:139], v[64:65], v[138:139]
	v_rcp_f32_e32 v141, v131
	v_cvt_pk_bf16_f32 v135, v138, v139
	v_add_u32_e32 v138, 0x80, v130
	v_ashrrev_i32_e32 v139, 31, v138
	v_lshlrev_b64 v[138:139], 10, v[138:139]
	v_lshl_add_u64 v[138:139], s[62:63], 0, v[138:139]
	v_lshl_add_u64 v[138:139], v[138:139], 0, s[22:23]
	v_pk_mul_f32 v[136:137], v[58:59], v[136:137]
	v_pk_mul_f32 v[140:141], v[60:61], v[140:141]
	v_lshl_add_u64 v[138:139], v[138:139], 0, s[78:79]
	v_mul_f32_e32 v131, 0xbfb8aa3b, v54
	v_cvt_pk_bf16_f32 v136, v136, v137
	v_cvt_pk_bf16_f32 v137, v140, v141
	v_lshl_add_u64 v[138:139], v[138:139], 0, v[132:133]
	v_exp_f32_e32 v131, v131
	v_mul_f32_e32 v140, 0xbfb8aa3b, v50
	v_exp_f32_e32 v140, v140
	global_store_dwordx4 v[138:139], v[134:137], off offset:-3072
	v_add_f32_e32 v131, 1.0, v131
	v_exp_f32_e32 v143, v142
	v_mul_f32_e32 v135, 0xbfb8aa3b, v55
	v_exp_f32_e32 v135, v135
	v_mul_f32_e32 v136, 0xbfb8aa3b, v51
	v_exp_f32_e32 v137, v136
	v_rcp_f32_e32 v134, v131
	v_add_f32_e32 v131, 1.0, v140
	v_rcp_f32_e32 v136, v131
	v_add_f32_e32 v131, 1.0, v135
	v_rcp_f32_e32 v135, v131
	v_add_f32_e32 v131, 1.0, v137
	v_mul_f32_e32 v137, 0xbfb8aa3b, v56
	v_exp_f32_e32 v140, v137
	v_mul_f32_e32 v137, 0xbfb8aa3b, v52
	v_exp_f32_e32 v141, v137
	v_rcp_f32_e32 v137, v131
	v_add_f32_e32 v131, 1.0, v140
	v_rcp_f32_e32 v140, v131
	v_add_f32_e32 v131, 1.0, v141
	v_mul_f32_e32 v141, 0xbfb8aa3b, v57
	v_exp_f32_e32 v141, v141
	v_rcp_f32_e32 v142, v131
	v_pk_mul_f32 v[134:135], v[54:55], v[134:135]
	v_pk_mul_f32 v[136:137], v[50:51], v[136:137]
	v_add_f32_e32 v131, 1.0, v141
	v_rcp_f32_e32 v141, v131
	v_add_f32_e32 v131, 1.0, v143
	v_rcp_f32_e32 v143, v131
	v_mul_f32_e32 v131, 0xbfb8aa3b, v46
	v_pk_mul_f32 v[140:141], v[56:57], v[140:141]
	v_cvt_pk_bf16_f32 v134, v134, v135
	v_pk_mul_f32 v[142:143], v[52:53], v[142:143]
	v_cvt_pk_bf16_f32 v135, v140, v141
	v_cvt_pk_bf16_f32 v136, v136, v137
	v_cvt_pk_bf16_f32 v137, v142, v143
	v_exp_f32_e32 v131, v131
	v_mul_f32_e32 v140, 0xbfb8aa3b, v42
	v_exp_f32_e32 v140, v140
	global_store_dwordx4 v[138:139], v[134:137], off offset:-2816
	v_add_f32_e32 v131, 1.0, v131
	v_mul_f32_e32 v142, 0xbfb8aa3b, v37
	v_mul_f32_e32 v135, 0xbfb8aa3b, v47
	v_exp_f32_e32 v135, v135
	v_mul_f32_e32 v136, 0xbfb8aa3b, v43
	v_exp_f32_e32 v137, v136
	v_rcp_f32_e32 v134, v131
	v_add_f32_e32 v131, 1.0, v140
	v_rcp_f32_e32 v136, v131
	v_add_f32_e32 v131, 1.0, v135
	v_rcp_f32_e32 v135, v131
	v_add_f32_e32 v131, 1.0, v137
	v_mul_f32_e32 v137, 0xbfb8aa3b, v48
	v_exp_f32_e32 v138, v137
	v_mul_f32_e32 v137, 0xbfb8aa3b, v44
	v_exp_f32_e32 v139, v137
	v_rcp_f32_e32 v137, v131
	v_add_f32_e32 v131, 1.0, v138
	v_rcp_f32_e32 v138, v131
	v_add_f32_e32 v131, 1.0, v139
	v_mul_f32_e32 v139, 0xbfb8aa3b, v49
	v_exp_f32_e32 v139, v139
	v_mul_f32_e32 v140, 0xbfb8aa3b, v45
	v_exp_f32_e32 v141, v140
	v_rcp_f32_e32 v140, v131
	v_add_f32_e32 v131, 1.0, v139
	v_rcp_f32_e32 v139, v131
	v_pk_mul_f32 v[134:135], v[46:47], v[134:135]
	v_add_f32_e32 v131, 1.0, v141
	v_cvt_pk_bf16_f32 v134, v134, v135
	v_pk_mul_f32 v[138:139], v[48:49], v[138:139]
	v_rcp_f32_e32 v141, v131
	v_cvt_pk_bf16_f32 v135, v138, v139
	v_add_u32_e32 v138, 0x90, v130
	v_ashrrev_i32_e32 v139, 31, v138
	v_lshlrev_b64 v[138:139], 10, v[138:139]
	v_lshl_add_u64 v[138:139], s[62:63], 0, v[138:139]
	v_lshl_add_u64 v[138:139], v[138:139], 0, s[22:23]
	v_pk_mul_f32 v[136:137], v[42:43], v[136:137]
	v_pk_mul_f32 v[140:141], v[44:45], v[140:141]
	v_lshl_add_u64 v[138:139], v[138:139], 0, s[78:79]
; __device__ __forceinline__ float fast_silu(float v) { return v * fast_sigmoid(v); }
; __device__ __forceinline__ u32x4 pack8f(const f32x4 a, const f32x4 b) { u32x4 w; w.x = cvt_pk_bf16(a[0], a[1]); w.y = cvt_pk_bf16(a[2], a[3]); w.z = cvt_pk_bf16(b[0], b[1]); w.w = cvt_pk_bf16(b[2], b[3]); return w; }
;     __device__ __forceinline__ void operator()(f32x4 (&acc)[2][2][4][2], const Unit& u, int wr, int wc, int fr, int fq) const {
;     ...
;                 for (int m = 0; m < 4; ++m) { const int rl = rl0 + 128 * ai + 16 * m;
; #pragma unroll
;                     for (int bj = 0; bj < 2; ++bj) { f32x4 a = acc[ai][bj][m][0], c = acc[ai][bj][m][1];
; #pragma unroll
;                         for (int i = 0; i < 4; ++i) { a[i] = fast_silu(a[i]); c[i] = fast_silu(c[i]); }
;                         *(u32x4*)(SG + (size_t)(u.pm * 256 + rl) * AW + (pn - 6) * 256 + 128 * bj + 32 * wc + 8 * fq) = pack8f(a, c); }
	v_mul_f32_e32 v131, 0xbfb8aa3b, v38
	v_cvt_pk_bf16_f32 v136, v136, v137
	v_cvt_pk_bf16_f32 v137, v140, v141
	v_lshl_add_u64 v[138:139], v[138:139], 0, v[132:133]
	v_exp_f32_e32 v131, v131
	v_mul_f32_e32 v140, 0xbfb8aa3b, v34
	v_exp_f32_e32 v140, v140
	global_store_dwordx4 v[138:139], v[134:137], off offset:-3072
	v_add_f32_e32 v131, 1.0, v131
	v_exp_f32_e32 v143, v142
	v_mul_f32_e32 v135, 0xbfb8aa3b, v39
	v_exp_f32_e32 v135, v135
	v_mul_f32_e32 v136, 0xbfb8aa3b, v35
	v_exp_f32_e32 v137, v136
	v_rcp_f32_e32 v134, v131
	v_add_f32_e32 v131, 1.0, v140
	v_rcp_f32_e32 v136, v131
	v_add_f32_e32 v131, 1.0, v135
	v_rcp_f32_e32 v135, v131
	v_add_f32_e32 v131, 1.0, v137
	v_mul_f32_e32 v137, 0xbfb8aa3b, v40
	v_exp_f32_e32 v140, v137
	v_mul_f32_e32 v137, 0xbfb8aa3b, v36
	v_exp_f32_e32 v141, v137
	v_rcp_f32_e32 v137, v131
	v_add_f32_e32 v131, 1.0, v140
	v_rcp_f32_e32 v140, v131
	v_add_f32_e32 v131, 1.0, v141
	v_mul_f32_e32 v141, 0xbfb8aa3b, v41
	v_exp_f32_e32 v141, v141
	v_rcp_f32_e32 v142, v131
	v_pk_mul_f32 v[134:135], v[38:39], v[134:135]
	v_pk_mul_f32 v[136:137], v[34:35], v[136:137]
	v_add_f32_e32 v131, 1.0, v141
	v_rcp_f32_e32 v141, v131
	v_add_f32_e32 v131, 1.0, v143
	v_rcp_f32_e32 v143, v131
	v_mul_f32_e32 v131, 0xbfb8aa3b, v30
	v_pk_mul_f32 v[140:141], v[40:41], v[140:141]
	v_cvt_pk_bf16_f32 v134, v134, v135
	v_pk_mul_f32 v[142:143], v[36:37], v[142:143]
	v_cvt_pk_bf16_f32 v135, v140, v141
	v_cvt_pk_bf16_f32 v136, v136, v137
	v_cvt_pk_bf16_f32 v137, v142, v143
	v_exp_f32_e32 v131, v131
	v_mul_f32_e32 v140, 0xbfb8aa3b, v26
	v_exp_f32_e32 v140, v140
	global_store_dwordx4 v[138:139], v[134:137], off offset:-2816
	v_add_f32_e32 v131, 1.0, v131
	v_mul_f32_e32 v142, 0xbfb8aa3b, v21
	v_mul_f32_e32 v135, 0xbfb8aa3b, v31
	v_exp_f32_e32 v135, v135
	v_mul_f32_e32 v136, 0xbfb8aa3b, v27
	v_exp_f32_e32 v137, v136
	v_rcp_f32_e32 v134, v131
	v_add_f32_e32 v131, 1.0, v140
	v_rcp_f32_e32 v136, v131
	v_add_f32_e32 v131, 1.0, v135
	v_rcp_f32_e32 v135, v131
	v_add_f32_e32 v131, 1.0, v137
	v_mul_f32_e32 v137, 0xbfb8aa3b, v32
	v_exp_f32_e32 v138, v137
	v_mul_f32_e32 v137, 0xbfb8aa3b, v28
	v_exp_f32_e32 v139, v137
	v_rcp_f32_e32 v137, v131
	v_add_f32_e32 v131, 1.0, v138
	v_rcp_f32_e32 v138, v131
	v_add_f32_e32 v131, 1.0, v139
	v_mul_f32_e32 v139, 0xbfb8aa3b, v33
	v_exp_f32_e32 v139, v139
	v_mul_f32_e32 v140, 0xbfb8aa3b, v29
	v_exp_f32_e32 v141, v140
	v_rcp_f32_e32 v140, v131
	v_add_f32_e32 v131, 1.0, v139
	v_rcp_f32_e32 v139, v131
	v_pk_mul_f32 v[134:135], v[30:31], v[134:135]
	v_add_f32_e32 v131, 1.0, v141
	v_cvt_pk_bf16_f32 v134, v134, v135
	v_pk_mul_f32 v[138:139], v[32:33], v[138:139]
	v_rcp_f32_e32 v141, v131
	v_cvt_pk_bf16_f32 v135, v138, v139
	v_add_u32_e32 v138, 0xa0, v130
	v_ashrrev_i32_e32 v139, 31, v138
	v_lshlrev_b64 v[138:139], 10, v[138:139]
	v_lshl_add_u64 v[138:139], s[62:63], 0, v[138:139]
	v_lshl_add_u64 v[138:139], v[138:139], 0, s[22:23]
	v_pk_mul_f32 v[136:137], v[26:27], v[136:137]
	v_pk_mul_f32 v[140:141], v[28:29], v[140:141]
	v_lshl_add_u64 v[138:139], v[138:139], 0, s[78:79]
	v_mul_f32_e32 v131, 0xbfb8aa3b, v22
	v_cvt_pk_bf16_f32 v136, v136, v137
	v_cvt_pk_bf16_f32 v137, v140, v141
	v_lshl_add_u64 v[138:139], v[138:139], 0, v[132:133]
	v_exp_f32_e32 v131, v131
	v_mul_f32_e32 v140, 0xbfb8aa3b, v18
	v_exp_f32_e32 v140, v140
	global_store_dwordx4 v[138:139], v[134:137], off offset:-3072
	v_add_f32_e32 v131, 1.0, v131
	v_exp_f32_e32 v143, v142
	v_mul_f32_e32 v135, 0xbfb8aa3b, v23
	v_exp_f32_e32 v135, v135
	v_mul_f32_e32 v136, 0xbfb8aa3b, v19
	v_exp_f32_e32 v137, v136
	v_rcp_f32_e32 v134, v131
	v_add_f32_e32 v131, 1.0, v140
	v_rcp_f32_e32 v136, v131
	v_add_f32_e32 v131, 1.0, v135
	v_rcp_f32_e32 v135, v131
	v_add_f32_e32 v131, 1.0, v137
	v_mul_f32_e32 v137, 0xbfb8aa3b, v24
	v_exp_f32_e32 v140, v137
	v_mul_f32_e32 v137, 0xbfb8aa3b, v20
; __device__ __forceinline__ float fast_silu(float v) { return v * fast_sigmoid(v); }
; __device__ __forceinline__ u32x4 pack8f(const f32x4 a, const f32x4 b) { u32x4 w; w.x = cvt_pk_bf16(a[0], a[1]); w.y = cvt_pk_bf16(a[2], a[3]); w.z = cvt_pk_bf16(b[0], b[1]); w.w = cvt_pk_bf16(b[2], b[3]); return w; }
;     __device__ __forceinline__ void operator()(f32x4 (&acc)[2][2][4][2], const Unit& u, int wr, int wc, int fr, int fq) const {
;     ...
;                 for (int m = 0; m < 4; ++m) { const int rl = rl0 + 128 * ai + 16 * m;
; #pragma unroll
;                     for (int bj = 0; bj < 2; ++bj) { f32x4 a = acc[ai][bj][m][0], c = acc[ai][bj][m][1];
; #pragma unroll
;                         for (int i = 0; i < 4; ++i) { a[i] = fast_silu(a[i]); c[i] = fast_silu(c[i]); }
;                         *(u32x4*)(SG + (size_t)(u.pm * 256 + rl) * AW + (pn - 6) * 256 + 128 * bj + 32 * wc + 8 * fq) = pack8f(a, c); }
	v_exp_f32_e32 v141, v137
	v_rcp_f32_e32 v137, v131
	v_add_f32_e32 v131, 1.0, v140
	v_rcp_f32_e32 v140, v131
	v_add_f32_e32 v131, 1.0, v141
	v_mul_f32_e32 v141, 0xbfb8aa3b, v25
	v_exp_f32_e32 v141, v141
	v_rcp_f32_e32 v142, v131
	v_pk_mul_f32 v[134:135], v[22:23], v[134:135]
	v_pk_mul_f32 v[136:137], v[18:19], v[136:137]
	v_add_f32_e32 v131, 1.0, v141
	v_rcp_f32_e32 v141, v131
	v_add_f32_e32 v131, 1.0, v143
	v_rcp_f32_e32 v143, v131
	v_mul_f32_e32 v131, 0xbfb8aa3b, v14
	v_pk_mul_f32 v[140:141], v[24:25], v[140:141]
	v_cvt_pk_bf16_f32 v134, v134, v135
	v_pk_mul_f32 v[142:143], v[20:21], v[142:143]
	v_cvt_pk_bf16_f32 v135, v140, v141
	v_cvt_pk_bf16_f32 v136, v136, v137
	v_cvt_pk_bf16_f32 v137, v142, v143
	v_exp_f32_e32 v131, v131
	v_mul_f32_e32 v140, 0xbfb8aa3b, v10
	v_exp_f32_e32 v140, v140
	global_store_dwordx4 v[138:139], v[134:137], off offset:-2816
	v_add_f32_e32 v131, 1.0, v131
	v_add_u32_e32 v130, 0xb0, v130
	v_mul_f32_e32 v135, 0xbfb8aa3b, v15
	v_exp_f32_e32 v135, v135
	v_mul_f32_e32 v136, 0xbfb8aa3b, v11
	v_exp_f32_e32 v137, v136
	v_rcp_f32_e32 v134, v131
	v_add_f32_e32 v131, 1.0, v140
	v_rcp_f32_e32 v136, v131
	v_add_f32_e32 v131, 1.0, v135
	v_rcp_f32_e32 v135, v131
	v_add_f32_e32 v131, 1.0, v137
	v_mul_f32_e32 v137, 0xbfb8aa3b, v16
	v_exp_f32_e32 v138, v137
	v_mul_f32_e32 v137, 0xbfb8aa3b, v12
	v_exp_f32_e32 v139, v137
	v_rcp_f32_e32 v137, v131
	v_add_f32_e32 v131, 1.0, v138
	v_rcp_f32_e32 v138, v131
	v_add_f32_e32 v131, 1.0, v139
	v_mul_f32_e32 v139, 0xbfb8aa3b, v17
	v_exp_f32_e32 v139, v139
	v_mul_f32_e32 v140, 0xbfb8aa3b, v13
	v_exp_f32_e32 v141, v140
	v_rcp_f32_e32 v140, v131
	v_add_f32_e32 v131, 1.0, v139
	v_rcp_f32_e32 v139, v131
	v_add_f32_e32 v131, 1.0, v141
	v_rcp_f32_e32 v141, v131
	v_ashrrev_i32_e32 v131, 31, v130
	v_lshlrev_b64 v[130:131], 10, v[130:131]
	v_lshl_add_u64 v[130:131], s[62:63], 0, v[130:131]
	v_lshl_add_u64 v[130:131], v[130:131], 0, s[22:23]
	v_pk_mul_f32 v[134:135], v[14:15], v[134:135]
	v_pk_mul_f32 v[138:139], v[16:17], v[138:139]
	v_lshl_add_u64 v[130:131], v[130:131], 0, s[78:79]
	v_pk_mul_f32 v[136:137], v[10:11], v[136:137]
	v_pk_mul_f32 v[140:141], v[12:13], v[140:141]
	v_cvt_pk_bf16_f32 v134, v134, v135
	v_cvt_pk_bf16_f32 v135, v138, v139
	v_lshl_add_u64 v[138:139], v[130:131], 0, v[132:133]
	v_mul_f32_e32 v131, 0xbfb8aa3b, v2
	v_mul_f32_e32 v132, 0xbfb8aa3b, v7
	v_cvt_pk_bf16_f32 v136, v136, v137
	v_cvt_pk_bf16_f32 v137, v140, v141
	v_exp_f32_e32 v131, v131
	v_exp_f32_e32 v133, v132
	v_mul_f32_e32 v132, 0xbfb8aa3b, v3
	global_store_dwordx4 v[138:139], v[134:137], off offset:-3072
	v_add_f32_e32 v131, 1.0, v131
	v_mul_f32_e32 v130, 0xbfb8aa3b, v6
	v_exp_f32_e32 v134, v132
	v_mul_f32_e32 v135, 0xbfb8aa3b, v4
	v_mul_f32_e32 v136, 0xbfb8aa3b, v9
	v_rcp_f32_e32 v132, v131
	v_add_f32_e32 v131, 1.0, v133
	v_add_f32_e32 v133, 1.0, v134
	v_mul_f32_e32 v134, 0xbfb8aa3b, v8
	v_exp_f32_e32 v135, v135
	v_exp_f32_e32 v137, v136
	v_mul_f32_e32 v136, 0xbfb8aa3b, v5
	v_exp_f32_e32 v130, v130
	v_exp_f32_e32 v134, v134
	v_exp_f32_e32 v140, v136
	v_add_f32_e32 v135, 1.0, v135
	v_add_f32_e32 v130, 1.0, v130
	v_add_f32_e32 v134, 1.0, v134
	v_rcp_f32_e32 v136, v135
	v_add_f32_e32 v135, 1.0, v137
	v_add_f32_e32 v137, 1.0, v140
	v_rcp_f32_e32 v130, v130
	v_rcp_f32_e32 v131, v131
	v_rcp_f32_e32 v133, v133
	v_rcp_f32_e32 v134, v134
	v_rcp_f32_e32 v135, v135
	v_rcp_f32_e32 v137, v137
	v_pk_mul_f32 v[130:131], v[6:7], v[130:131]
	v_pk_mul_f32 v[132:133], v[2:3], v[132:133]
	v_pk_mul_f32 v[134:135], v[8:9], v[134:135]
	v_pk_mul_f32 v[136:137], v[4:5], v[136:137]
	v_cvt_pk_bf16_f32 v130, v130, v131
	v_cvt_pk_bf16_f32 v131, v134, v135
	v_cvt_pk_bf16_f32 v132, v132, v133
	v_cvt_pk_bf16_f32 v133, v136, v137
	global_store_dwordx4 v[138:139], v[130:133], off offset:-2816
	s_branch .LBB0_239

; __device__ __forceinline__ u32x4 pack8f(const f32x4 a, const f32x4 b) { u32x4 w; w.x = cvt_pk_bf16(a[0], a[1]); w.y = cvt_pk_bf16(a[2], a[3]); w.z = cvt_pk_bf16(b[0], b[1]); w.w = cvt_pk_bf16(b[2], b[3]); return w; }
;     __device__ __forceinline__ void operator()(f32x4 (&acc)[2][2][4][2], const Unit& u, int wr, int wc, int fr, int fq) const {
;     ...
;         } else if (pn < 6) {
; #pragma unroll
;             for (int ai = 0; ai < 2; ++ai)
; #pragma unroll
;                 for (int m = 0; m < 4; ++m) { const int rl = rl0 + 128 * ai + 16 * m;
; #pragma unroll
;                     for (int bj = 0; bj < 2; ++bj)
;                         *(u32x4*)(VI + vimg_off(b, (pn - 4) * 2 + bj, s0 + rl + NMETA, 32 * wc + 8 * fq)) = pack8f(acc[ai][bj][m][0], acc[ai][bj][m][1]);
;                 }
.LBB0_171:
	s_andn2_b64 vcc, exec, s[88:89]
	s_cbranch_vccnz .LBB0_173
	v_add_u32_e32 v144, s83, v166
	v_lshlrev_b32_e32 v132, 1, v166
	s_lshl_b32 s11, s10, 1
	v_add_u32_e32 v130, 16, v144
	v_readlane_b32 s18, v236, 22
	v_and_b32_e32 v145, 8, v132
	s_add_i32 s11, s11, -8
	v_lshl_add_u32 v131, v200, 3, s18
	s_lshl_b32 s18, s81, 2
	v_ashrrev_i32_e32 v136, 6, v130
	v_and_or_b32 v130, v130, 48, v145
	s_or_b32 s11, s18, s11
	v_ashrrev_i32_e32 v167, 5, v131
	v_ashrrev_i32_e32 v137, 31, v136
	v_lshrrev_b32_e32 v130, 1, v130
	v_lshrrev_b32_e32 v132, 1, v166
	v_and_b32_e32 v131, 3, v166
	v_add_lshl_u32 v130, v130, v167, 8
	v_mad_i64_i32 v[138:139], s[88:89], s11, v197, v[136:137]
	v_and_or_b32 v142, v132, 4, v131
	v_ashrrev_i32_e32 v131, 31, v130
	v_lshlrev_b64 v[138:139], 14, v[138:139]
	s_or_b32 s22, s11, 1
	v_lshl_add_u64 v[138:139], s[60:61], 0, v[138:139]
	v_lshlrev_b64 v[140:141], 1, v[130:131]
	v_mad_i64_i32 v[136:137], s[88:89], s22, v197, v[136:137]
	v_lshl_add_u64 v[130:131], v[138:139], 0, v[140:141]
	v_lshlrev_b32_e32 v154, 6, v142
	v_lshlrev_b64 v[136:137], 14, v[136:137]
	v_lshl_add_u64 v[138:139], v[130:131], 0, v[154:155]
	v_lshlrev_b32_e32 v130, 4, v200
	v_lshl_add_u64 v[136:137], s[60:61], 0, v[136:137]
	v_and_b32_e32 v130, 48, v130
	v_mov_b32_e32 v131, v155
	v_lshl_add_u64 v[136:137], v[136:137], 0, v[140:141]
	v_cvt_pk_bf16_f32 v132, v126, v127
	v_cvt_pk_bf16_f32 v133, v128, v129
	v_cvt_pk_bf16_f32 v134, v122, v123
	v_cvt_pk_bf16_f32 v135, v124, v125
	v_lshl_add_u64 v[138:139], v[138:139], 0, v[130:131]
	v_lshl_add_u64 v[136:137], v[136:137], 0, v[154:155]
	global_store_dwordx4 v[138:139], v[132:135], off
	v_lshl_add_u64 v[136:137], v[136:137], 0, v[130:131]
	s_nop 0
	v_cvt_pk_bf16_f32 v132, v118, v119
	v_cvt_pk_bf16_f32 v133, v120, v121
	v_cvt_pk_bf16_f32 v134, v114, v115
	v_cvt_pk_bf16_f32 v135, v116, v117
	global_store_dwordx4 v[136:137], v[132:135], off
	s_nop 1
	v_add_u32_e32 v132, 32, v144
	v_ashrrev_i32_e32 v136, 6, v132
	v_and_or_b32 v132, v132, 48, v145
	v_ashrrev_i32_e32 v137, 31, v136
	v_lshrrev_b32_e32 v132, 1, v132
	v_add_lshl_u32 v138, v132, v167, 8
	v_mad_i64_i32 v[142:143], s[88:89], s11, v197, v[136:137]
	v_ashrrev_i32_e32 v139, 31, v138
	v_lshlrev_b64 v[142:143], 14, v[142:143]
	v_mad_i64_i32 v[136:137], s[88:89], s22, v197, v[136:137]
	v_lshl_add_u64 v[142:143], s[60:61], 0, v[142:143]
	v_lshlrev_b64 v[138:139], 1, v[138:139]
	v_lshlrev_b64 v[136:137], 14, v[136:137]
	v_lshl_add_u64 v[142:143], v[142:143], 0, v[138:139]
	v_lshl_add_u64 v[136:137], s[60:61], 0, v[136:137]
	v_lshl_add_u64 v[142:143], v[142:143], 0, v[154:155]
	v_lshl_add_u64 v[136:137], v[136:137], 0, v[138:139]
	v_cvt_pk_bf16_f32 v132, v110, v111
	v_cvt_pk_bf16_f32 v133, v112, v113
	v_cvt_pk_bf16_f32 v134, v106, v107
	v_cvt_pk_bf16_f32 v135, v108, v109
	v_lshl_add_u64 v[142:143], v[142:143], 0, v[130:131]
	v_lshl_add_u64 v[136:137], v[136:137], 0, v[154:155]
	global_store_dwordx4 v[142:143], v[132:135], off
	v_lshl_add_u64 v[136:137], v[136:137], 0, v[130:131]
	s_nop 0
	v_cvt_pk_bf16_f32 v132, v102, v103
	v_cvt_pk_bf16_f32 v133, v104, v105
	v_cvt_pk_bf16_f32 v134, v98, v99
	v_cvt_pk_bf16_f32 v135, v100, v101
	global_store_dwordx4 v[136:137], v[132:135], off
	s_nop 1
	v_add_u32_e32 v132, 48, v144
	v_ashrrev_i32_e32 v136, 6, v132
	v_and_or_b32 v132, v132, 48, v145
	v_ashrrev_i32_e32 v137, 31, v136
	v_lshrrev_b32_e32 v132, 1, v132
	v_add_lshl_u32 v138, v132, v167, 8
	v_mad_i64_i32 v[142:143], s[88:89], s11, v197, v[136:137]
	v_ashrrev_i32_e32 v139, 31, v138
	v_lshlrev_b64 v[142:143], 14, v[142:143]
	v_mad_i64_i32 v[136:137], s[88:89], s22, v197, v[136:137]
	v_lshl_add_u64 v[142:143], s[60:61], 0, v[142:143]
	v_lshlrev_b64 v[138:139], 1, v[138:139]
	v_lshlrev_b64 v[136:137], 14, v[136:137]
	v_lshl_add_u64 v[142:143], v[142:143], 0, v[138:139]
	v_lshl_add_u64 v[136:137], s[60:61], 0, v[136:137]
	v_lshl_add_u64 v[142:143], v[142:143], 0, v[154:155]
	v_lshl_add_u64 v[136:137], v[136:137], 0, v[138:139]
	v_cvt_pk_bf16_f32 v132, v94, v95
	v_cvt_pk_bf16_f32 v133, v96, v97
	v_cvt_pk_bf16_f32 v134, v90, v91
	v_cvt_pk_bf16_f32 v135, v92, v93
	v_lshl_add_u64 v[142:143], v[142:143], 0, v[130:131]
	v_lshl_add_u64 v[136:137], v[136:137], 0, v[154:155]
	global_store_dwordx4 v[142:143], v[132:135], off
	v_lshl_add_u64 v[136:137], v[136:137], 0, v[130:131]
	s_nop 0
	v_cvt_pk_bf16_f32 v132, v86, v87
	v_cvt_pk_bf16_f32 v133, v88, v89
	v_cvt_pk_bf16_f32 v134, v82, v83
	v_cvt_pk_bf16_f32 v135, v84, v85
	global_store_dwordx4 v[136:137], v[132:135], off
	s_nop 1
	v_add_u32_e32 v132, 64, v144
	v_ashrrev_i32_e32 v136, 6, v132
	v_and_or_b32 v132, v132, 48, v145
	v_ashrrev_i32_e32 v137, 31, v136
	v_lshrrev_b32_e32 v132, 1, v132
	v_add_lshl_u32 v138, v132, v167, 8
	v_mad_i64_i32 v[142:143], s[88:89], s11, v197, v[136:137]
	v_ashrrev_i32_e32 v139, 31, v138
	v_lshlrev_b64 v[142:143], 14, v[142:143]
	v_mad_i64_i32 v[136:137], s[88:89], s22, v197, v[136:137]
	v_lshl_add_u64 v[142:143], s[60:61], 0, v[142:143]
	v_lshlrev_b64 v[138:139], 1, v[138:139]
	v_lshlrev_b64 v[136:137], 14, v[136:137]
	v_lshl_add_u64 v[142:143], v[142:143], 0, v[138:139]
	v_lshl_add_u64 v[136:137], s[60:61], 0, v[136:137]
	v_lshl_add_u64 v[142:143], v[142:143], 0, v[154:155]
	v_lshl_add_u64 v[136:137], v[136:137], 0, v[138:139]
	v_cvt_pk_bf16_f32 v132, v78, v79
	v_cvt_pk_bf16_f32 v133, v80, v81
	v_cvt_pk_bf16_f32 v134, v74, v75
	v_cvt_pk_bf16_f32 v135, v76, v77
; __device__ __forceinline__ u32x4 pack8f(const f32x4 a, const f32x4 b) { u32x4 w; w.x = cvt_pk_bf16(a[0], a[1]); w.y = cvt_pk_bf16(a[2], a[3]); w.z = cvt_pk_bf16(b[0], b[1]); w.w = cvt_pk_bf16(b[2], b[3]); return w; }
;     __device__ __forceinline__ void operator()(f32x4 (&acc)[2][2][4][2], const Unit& u, int wr, int wc, int fr, int fq) const {
;     ...
;                 for (int m = 0; m < 4; ++m) { const int rl = rl0 + 128 * ai + 16 * m;
; #pragma unroll
;                     for (int bj = 0; bj < 2; ++bj)
;                         *(u32x4*)(VI + vimg_off(b, (pn - 4) * 2 + bj, s0 + rl + NMETA, 32 * wc + 8 * fq)) = pack8f(acc[ai][bj][m][0], acc[ai][bj][m][1]);
;                 }
	v_lshl_add_u64 v[142:143], v[142:143], 0, v[130:131]
	v_lshl_add_u64 v[136:137], v[136:137], 0, v[154:155]
	global_store_dwordx4 v[142:143], v[132:135], off
	v_lshl_add_u64 v[136:137], v[136:137], 0, v[130:131]
	s_nop 0
	v_cvt_pk_bf16_f32 v132, v70, v71
	v_cvt_pk_bf16_f32 v133, v72, v73
	v_cvt_pk_bf16_f32 v134, v66, v67
	v_cvt_pk_bf16_f32 v135, v68, v69
	global_store_dwordx4 v[136:137], v[132:135], off
	s_nop 1
	v_add_u32_e32 v132, 0x90, v144
	v_ashrrev_i32_e32 v136, 6, v132
	v_ashrrev_i32_e32 v137, 31, v136
	v_mad_i64_i32 v[138:139], s[88:89], s11, v197, v[136:137]
	v_lshlrev_b64 v[138:139], 14, v[138:139]
	v_mad_i64_i32 v[136:137], s[88:89], s22, v197, v[136:137]
	v_lshl_add_u64 v[138:139], s[60:61], 0, v[138:139]
	v_lshlrev_b64 v[136:137], 14, v[136:137]
	v_lshl_add_u64 v[138:139], v[138:139], 0, v[140:141]
	v_lshl_add_u64 v[136:137], s[60:61], 0, v[136:137]
	v_lshl_add_u64 v[138:139], v[138:139], 0, v[154:155]
	v_lshl_add_u64 v[136:137], v[136:137], 0, v[140:141]
	v_cvt_pk_bf16_f32 v132, v62, v63
	v_cvt_pk_bf16_f32 v133, v64, v65
	v_cvt_pk_bf16_f32 v134, v58, v59
	v_cvt_pk_bf16_f32 v135, v60, v61
	v_lshl_add_u64 v[138:139], v[138:139], 0, v[130:131]
	v_lshl_add_u64 v[136:137], v[136:137], 0, v[154:155]
	global_store_dwordx4 v[138:139], v[132:135], off
	v_lshl_add_u64 v[136:137], v[136:137], 0, v[130:131]
	s_nop 0
	v_cvt_pk_bf16_f32 v132, v54, v55
	v_cvt_pk_bf16_f32 v133, v56, v57
	v_cvt_pk_bf16_f32 v134, v50, v51
	v_cvt_pk_bf16_f32 v135, v52, v53
	global_store_dwordx4 v[136:137], v[132:135], off
	s_nop 1
	v_add_u32_e32 v132, 0xa0, v144
	v_ashrrev_i32_e32 v136, 6, v132
	v_and_or_b32 v132, v132, 48, v145
	v_ashrrev_i32_e32 v137, 31, v136
	v_lshrrev_b32_e32 v132, 1, v132
	v_add_lshl_u32 v138, v132, v167, 8
	v_mad_i64_i32 v[140:141], s[88:89], s11, v197, v[136:137]
	v_ashrrev_i32_e32 v139, 31, v138
	v_lshlrev_b64 v[140:141], 14, v[140:141]
	v_mad_i64_i32 v[136:137], s[88:89], s22, v197, v[136:137]
	v_lshl_add_u64 v[140:141], s[60:61], 0, v[140:141]
	v_lshlrev_b64 v[138:139], 1, v[138:139]
	v_lshlrev_b64 v[136:137], 14, v[136:137]
	v_lshl_add_u64 v[140:141], v[140:141], 0, v[138:139]
	v_lshl_add_u64 v[136:137], s[60:61], 0, v[136:137]
	v_lshl_add_u64 v[140:141], v[140:141], 0, v[154:155]
	v_lshl_add_u64 v[136:137], v[136:137], 0, v[138:139]
	v_cvt_pk_bf16_f32 v132, v46, v47
	v_cvt_pk_bf16_f32 v133, v48, v49
	v_cvt_pk_bf16_f32 v134, v42, v43
	v_cvt_pk_bf16_f32 v135, v44, v45
	v_lshl_add_u64 v[140:141], v[140:141], 0, v[130:131]
	v_lshl_add_u64 v[136:137], v[136:137], 0, v[154:155]
	global_store_dwordx4 v[140:141], v[132:135], off
	v_lshl_add_u64 v[136:137], v[136:137], 0, v[130:131]
	s_nop 0
	v_cvt_pk_bf16_f32 v132, v38, v39
	v_cvt_pk_bf16_f32 v133, v40, v41
	v_cvt_pk_bf16_f32 v134, v34, v35
	v_cvt_pk_bf16_f32 v135, v36, v37
	global_store_dwordx4 v[136:137], v[132:135], off
	s_nop 1
	v_add_u32_e32 v132, 0xb0, v144
	v_ashrrev_i32_e32 v136, 6, v132
	v_and_or_b32 v132, v132, 48, v145
	v_ashrrev_i32_e32 v137, 31, v136
	v_lshrrev_b32_e32 v132, 1, v132
	v_add_lshl_u32 v138, v132, v167, 8
	v_mad_i64_i32 v[140:141], s[88:89], s11, v197, v[136:137]
	v_ashrrev_i32_e32 v139, 31, v138
	v_lshlrev_b64 v[140:141], 14, v[140:141]
	v_mad_i64_i32 v[136:137], s[88:89], s22, v197, v[136:137]
	v_lshl_add_u64 v[140:141], s[60:61], 0, v[140:141]
	v_lshlrev_b64 v[138:139], 1, v[138:139]
	v_lshlrev_b64 v[136:137], 14, v[136:137]
	v_lshl_add_u64 v[140:141], v[140:141], 0, v[138:139]
	v_lshl_add_u64 v[136:137], s[60:61], 0, v[136:137]
	v_lshl_add_u64 v[140:141], v[140:141], 0, v[154:155]
	v_lshl_add_u64 v[136:137], v[136:137], 0, v[138:139]
	v_cvt_pk_bf16_f32 v132, v30, v31
	v_cvt_pk_bf16_f32 v133, v32, v33
	v_cvt_pk_bf16_f32 v134, v26, v27
	v_cvt_pk_bf16_f32 v135, v28, v29
	v_lshl_add_u64 v[140:141], v[140:141], 0, v[130:131]
	v_lshl_add_u64 v[136:137], v[136:137], 0, v[154:155]
	global_store_dwordx4 v[140:141], v[132:135], off
	v_lshl_add_u64 v[136:137], v[136:137], 0, v[130:131]
	s_nop 0
	v_cvt_pk_bf16_f32 v132, v22, v23
	v_cvt_pk_bf16_f32 v133, v24, v25
	v_cvt_pk_bf16_f32 v134, v18, v19
	v_cvt_pk_bf16_f32 v135, v20, v21
	global_store_dwordx4 v[136:137], v[132:135], off
	s_nop 1
	v_add_u32_e32 v132, 0xc0, v144
	v_ashrrev_i32_e32 v136, 6, v132
	v_and_or_b32 v132, v132, 48, v145
	v_ashrrev_i32_e32 v137, 31, v136
	v_lshrrev_b32_e32 v132, 1, v132
	v_add_lshl_u32 v138, v132, v167, 8
	v_mad_i64_i32 v[140:141], s[88:89], s11, v197, v[136:137]
	v_ashrrev_i32_e32 v139, 31, v138
	v_lshlrev_b64 v[140:141], 14, v[140:141]
	v_mad_i64_i32 v[136:137], s[88:89], s22, v197, v[136:137]
	v_lshl_add_u64 v[140:141], s[60:61], 0, v[140:141]
	v_lshlrev_b64 v[138:139], 1, v[138:139]
	v_lshlrev_b64 v[136:137], 14, v[136:137]
	v_lshl_add_u64 v[140:141], v[140:141], 0, v[138:139]
	v_lshl_add_u64 v[136:137], s[60:61], 0, v[136:137]
	v_lshl_add_u64 v[140:141], v[140:141], 0, v[154:155]
	v_lshl_add_u64 v[136:137], v[136:137], 0, v[138:139]
	v_cvt_pk_bf16_f32 v132, v14, v15
	v_cvt_pk_bf16_f32 v133, v16, v17
	v_cvt_pk_bf16_f32 v134, v10, v11
	v_cvt_pk_bf16_f32 v135, v12, v13
	v_lshl_add_u64 v[140:141], v[140:141], 0, v[130:131]
	v_lshl_add_u64 v[136:137], v[136:137], 0, v[154:155]
	global_store_dwordx4 v[140:141], v[132:135], off
	v_lshl_add_u64 v[130:131], v[136:137], 0, v[130:131]
	s_nop 0
	v_cvt_pk_bf16_f32 v132, v6, v7
	v_cvt_pk_bf16_f32 v133, v8, v9
	v_cvt_pk_bf16_f32 v134, v2, v3
	v_cvt_pk_bf16_f32 v135, v4, v5
	global_store_dwordx4 v[130:131], v[132:135], off
	s_branch .LBB0_239
